# v49 + skip the register restore after a residual Y store pair when the data registers are dead (8 of 47 pairs)
# speedup vs baseline: 1.0031x; 1.0031x over previous
; __device__ __forceinline__ size_t blk_off(int r, int c, int K) { return (size_t)(r >> 8) * 256 * K + (size_t)(c >> 6) * (256 * 64) + (size_t)((r & 255) * 64 + (c & 63)); }
; __device__ __forceinline__ u32x4 pack8(const f32x4 a, const f32x4 b) { u32x4 w; w.x = cvt_pk_bf16(a[0], a[1]); w.y = cvt_pk_bf16(a[2], a[3]); w.z = cvt_pk_bf16(b[0], b[1]); w.w = cvt_pk_bf16(b[2], b[3]); return w; }
;     __device__ __forceinline__ void operator()(const f32x4 (&acc)[2][2][4][2], const pg8::Unit& u, int wr, int wc, int fr, int fq) const {
;     ...
;             for (int m = 0; m < 4; ++m) { const int row = row0 + ai * 128 + m * 16; const float mu = mu4[m], rs = rs4[m];
;                 f32x4 yv[2][2], gq[2][2], bq_[2][2];
; #pragma unroll
;                 for (int bj = 0; bj < 2; ++bj)
; #pragma unroll
;                     for (int n = 0; n < 2; ++n) { yv[bj][n] = *(const f32x4*)(Yin + (size_t)row * D_ + col0 + bj * 128 + 4 * n); gq[bj][n] = *(const f32x4*)(g + col0 + bj * 128 + 4 * n); bq_[bj][n] = *(const f32x4*)(b + col0 + bj * 128 + 4 * n); }
;                 asm volatile("" ::: "memory");
;                 float s1 = 0.f, s2 = 0.f;
; #pragma unroll
;                 for (int bj = 0; bj < 2; ++bj) { float* yp = Y + (size_t)row * D_ + col0 + bj * 128; f32x4 v[2];
; #pragma unroll
;                     for (int n = 0; n < 2; ++n) { v[n] = (((yv[bj][n] - mu) * rs) * gq[bj][n] + bq_[bj][n]) * ALPHA_ + acc[ai][bj][m][n] * sc;
;                         *(f32x4*)(yp + 4 * n) = v[n]; s1 += (v[n][0] + v[n][1]) + (v[n][2] + v[n][3]); s2 += (v[n][0] * v[n][0] + v[n][1] * v[n][1]) + (v[n][2] * v[n][2] + v[n][3] * v[n][3]); }
;                     *(u32x4*)(Yb + blk_off(row, col0 + bj * 128, D_)) = pack8(v[0], v[1]); }
.LBB0_382:
	s_or_b64 exec, exec, s[26:27]
	v_pk_add_f32 v[50:51], v[70:71], v[72:73]
	s_mov_b32 s2, 0x3a800000
	v_pk_mul_f32 v[92:93], v[50:51], s[2:3] op_sel_hi:[1,0]
	s_mov_b32 s2, 0x800000
	v_fma_f32 v0, -v93, v93, v92
	v_max_f32_e32 v0, 0, v0
	v_add_f32_e32 v0, 0x3727c5ac, v0
	v_cmp_gt_f32_e32 vcc, s2, v0
	v_mul_f32_e32 v50, 0x4b800000, v0
	v_lshlrev_b64 v[120:121], 12, v[94:95]
	v_cndmask_b32_e32 v0, v0, v50, vcc
	v_rsq_f32_e32 v0, v0
	s_movk_i32 s2, 0x37c0
	s_load_dwordx16 s[60:75], s[34:35], 0x38
	v_mul_f32_e32 v50, 0x45800000, v0
	v_cndmask_b32_e32 v92, v0, v50, vcc
	v_lshl_add_u64 v[50:51], s[12:13], 0, v[120:121]
	v_lshl_add_u64 v[54:55], v[50:51], 0, v[152:153]
	global_load_dwordx4 v[96:99], v[54:55], off offset:16
	global_load_dwordx4 v[100:103], v[54:55], off
	global_load_dwordx4 v[104:107], v[154:155], off offset:16
	global_load_dwordx4 v[108:111], v[154:155], off
	global_load_dwordx4 v[112:115], v[156:157], off offset:16
	global_load_dwordx4 v[116:119], v[156:157], off
	global_load_dwordx4 v[50:53], v[54:55], off offset:528
	global_load_dwordx4 v[70:73], v[54:55], off offset:512
	s_nop 0
	global_load_dwordx4 v[54:57], v[154:155], off offset:528
	global_load_dwordx4 v[62:65], v[154:155], off offset:512
	global_load_dwordx4 v[58:61], v[156:157], off offset:528
	global_load_dwordx4 v[66:69], v[156:157], off offset:512
	v_lshlrev_b32_e32 v0, 6, v94
	v_and_or_b32 v0, v0, s2, v194
	s_mov_b32 s2, 0x3fd744fd
	s_waitcnt lgkmcnt(0)
	v_lshl_add_u64 v[94:95], s[74:75], 0, v[120:121]
	v_lshlrev_b32_e32 v0, 1, v0
	v_lshl_add_u64 v[94:95], v[94:95], 0, v[152:153]
	s_waitcnt vmcnt(10)
	v_sub_f32_e32 v103, v103, v93
	v_sub_f32_e32 v102, v102, v93
	v_sub_f32_e32 v101, v101, v93
	v_sub_f32_e32 v100, v100, v93
	v_pk_mul_f32 v[100:101], v[92:93], v[100:101] op_sel_hi:[0,1]
	v_pk_mul_f32 v[102:103], v[92:93], v[102:103] op_sel_hi:[0,1]
	s_waitcnt vmcnt(6)
	v_pk_fma_f32 v[102:103], v[110:111], v[102:103], v[118:119]
	v_pk_fma_f32 v[100:101], v[108:109], v[100:101], v[116:117]
	v_pk_mul_f32 v[102:103], v[102:103], s[2:3] op_sel_hi:[1,0]
	v_pk_mul_f32 v[100:101], v[100:101], s[2:3] op_sel_hi:[1,0]
	v_pk_fma_f32 v[102:103], v[48:49], 0.5, v[102:103] op_sel_hi:[1,0,1]
	v_pk_fma_f32 v[100:101], v[46:47], 0.5, v[100:101] op_sel_hi:[1,0,1]
	v_add_f32_e32 v47, v102, v103
	v_add_f32_e32 v46, v100, v101
	v_add_f32_e32 v46, v46, v47
	v_add_f32_e32 v108, 0, v46
	v_mul_f32_e32 v46, v101, v101
	v_mul_f32_e32 v47, v103, v103
	v_fmac_f32_e32 v46, v100, v100
	v_fmac_f32_e32 v47, v102, v102
	v_add_f32_e32 v109, v46, v47
	v_sub_f32_e32 v47, v99, v93
	v_sub_f32_e32 v46, v98, v93
	v_sub_f32_e32 v49, v97, v93
	v_sub_f32_e32 v48, v96, v93
	v_pk_mul_f32 v[48:49], v[92:93], v[48:49] op_sel_hi:[0,1]
	v_pk_mul_f32 v[46:47], v[92:93], v[46:47] op_sel_hi:[0,1]
	v_pk_fma_f32 v[46:47], v[106:107], v[46:47], v[114:115]
	v_pk_fma_f32 v[48:49], v[104:105], v[48:49], v[112:113]
	v_pk_mul_f32 v[46:47], v[46:47], s[2:3] op_sel_hi:[1,0]
	v_pk_mul_f32 v[48:49], v[48:49], s[2:3] op_sel_hi:[1,0]
	v_pk_fma_f32 v[98:99], v[44:45], 0.5, v[46:47] op_sel_hi:[1,0,1]
	v_pk_fma_f32 v[96:97], v[42:43], 0.5, v[48:49] op_sel_hi:[1,0,1]
	v_add_f32_e32 v43, v98, v99
	v_add_f32_e32 v42, v96, v97
	v_add_f32_e32 v42, v42, v43
	v_add_f32_e32 v47, v108, v42
	v_mul_f32_e32 v42, v97, v97
	v_mul_f32_e32 v43, v99, v99
	v_fmac_f32_e32 v42, v96, v96
	v_fmac_f32_e32 v43, v98, v98
	v_add_f32_e32 v42, v42, v43
	v_add_f32_e32 v46, v109, v42
	v_cvt_pk_bf16_f32 v42, v100, v101
	v_cvt_pk_bf16_f32 v43, v102, v103
	v_cvt_pk_bf16_f32 v44, v96, v97
	v_cvt_pk_bf16_f32 v45, v98, v99
	v_lshl_add_u64 v[48:49], v[80:81], 0, v[0:1]
	s_nop 0
	s_nop 1
	v_bfe_u32 v105, v227, 4, 2
	v_sub_u32_e32 v104, 0, v105
	v_lshlrev_b32_e32 v104, 4, v104
	v_ashrrev_i32_e32 v105, 31, v104
	v_lshl_add_u64 v[104:105], v[94:95], 0, v[104:105]
	v_permlane16_swap_b32_e32 v100, v96
	v_permlane16_swap_b32_e32 v101, v97
	v_permlane16_swap_b32_e32 v102, v98
	v_permlane16_swap_b32_e32 v103, v99
	v_permlane32_swap_b32_e32 v100, v96
	v_permlane32_swap_b32_e32 v101, v97
	v_permlane32_swap_b32_e32 v102, v98
	v_permlane32_swap_b32_e32 v103, v99
	v_mov_b32_e32 v108, v100
	v_mov_b32_e32 v109, v101
	v_mov_b32_e32 v110, v102
	v_mov_b32_e32 v111, v103
	v_bfe_u32 v106, v227, 3, 1
	v_mul_i32_i24_e32 v106, 0xffff8040, v106
	v_ashrrev_i32_e32 v107, 31, v106
	v_lshl_add_u64 v[104:105], v[104:105], 0, v[106:107]
	v_mov_b32_e32 v106, 0x8000
	v_mov_b32_e32 v107, 0
	v_lshl_add_u64 v[106:107], v[104:105], 0, v[106:107]
	v_mov_b32_dpp v100, v96 row_ror:8 row_mask:0xf bank_mask:0xc
	v_mov_b32_dpp v101, v97 row_ror:8 row_mask:0xf bank_mask:0xc
	v_mov_b32_dpp v102, v98 row_ror:8 row_mask:0xf bank_mask:0xc
	v_mov_b32_dpp v103, v99 row_ror:8 row_mask:0xf bank_mask:0xc
	v_mov_b32_dpp v96, v108 row_ror:8 row_mask:0xf bank_mask:0x3
	v_mov_b32_dpp v97, v109 row_ror:8 row_mask:0xf bank_mask:0x3
	v_mov_b32_dpp v98, v110 row_ror:8 row_mask:0xf bank_mask:0x3
	v_mov_b32_dpp v99, v111 row_ror:8 row_mask:0xf bank_mask:0x3
	global_store_dwordx4 v[104:105], v[100:103], off
	global_store_dwordx4 v[106:107], v[96:99], off
	s_nop 1
	global_store_dwordx4 v[48:49], v[42:45], off
	s_waitcnt vmcnt(7)
	s_nop 0
	v_sub_f32_e32 v43, v73, v93
	v_sub_f32_e32 v42, v72, v93
	v_sub_f32_e32 v45, v71, v93
	v_sub_f32_e32 v44, v70, v93
	v_pk_mul_f32 v[44:45], v[92:93], v[44:45] op_sel_hi:[0,1]
	v_pk_mul_f32 v[42:43], v[92:93], v[42:43] op_sel_hi:[0,1]
	s_waitcnt vmcnt(3)
; __device__ __forceinline__ float xsum16(float v) { const auto r = __builtin_amdgcn_permlane16_swap(__float_as_uint(v), __float_as_uint(v), false, false); return __uint_as_float(r[0]) + __uint_as_float(r[1]); }
; __device__ __forceinline__ float xsum32(float v) { const auto r = __builtin_amdgcn_permlane32_swap(__float_as_uint(v), __float_as_uint(v), false, false); return __uint_as_float(r[0]) + __uint_as_float(r[1]); }
; __device__ __forceinline__ size_t blk_off(int r, int c, int K) { return (size_t)(r >> 8) * 256 * K + (size_t)(c >> 6) * (256 * 64) + (size_t)((r & 255) * 64 + (c & 63)); }
; __device__ __forceinline__ u32x4 pack8(const f32x4 a, const f32x4 b) { u32x4 w; w.x = cvt_pk_bf16(a[0], a[1]); w.y = cvt_pk_bf16(a[2], a[3]); w.z = cvt_pk_bf16(b[0], b[1]); w.w = cvt_pk_bf16(b[2], b[3]); return w; }
;     __device__ __forceinline__ void operator()(const f32x4 (&acc)[2][2][4][2], const pg8::Unit& u, int wr, int wc, int fr, int fq) const {
;     ...
;                 for (int bj = 0; bj < 2; ++bj) { float* yp = Y + (size_t)row * D_ + col0 + bj * 128; f32x4 v[2];
; #pragma unroll
;                     for (int n = 0; n < 2; ++n) { v[n] = (((yv[bj][n] - mu) * rs) * gq[bj][n] + bq_[bj][n]) * ALPHA_ + acc[ai][bj][m][n] * sc;
;                         *(f32x4*)(yp + 4 * n) = v[n]; s1 += (v[n][0] + v[n][1]) + (v[n][2] + v[n][3]); s2 += (v[n][0] * v[n][0] + v[n][1] * v[n][1]) + (v[n][2] * v[n][2] + v[n][3] * v[n][3]); }
;                     *(u32x4*)(Yb + blk_off(row, col0 + bj * 128, D_)) = pack8(v[0], v[1]); }
;                 s1 = xsum32(xsum16(s1)); s2 = xsum32(xsum16(s2));
;                 if (fq == 0) *(f32x2*)(stn + (size_t)row * 32 + (u.pn * 4 + wc) * 2) = (f32x2){s1, s2}; asm volatile("" ::: "memory"); } }
	v_pk_fma_f32 v[42:43], v[64:65], v[42:43], v[68:69]
	v_pk_fma_f32 v[44:45], v[62:63], v[44:45], v[66:67]
	v_pk_mul_f32 v[42:43], v[42:43], s[2:3] op_sel_hi:[1,0]
	v_pk_mul_f32 v[44:45], v[44:45], s[2:3] op_sel_hi:[1,0]
	v_pk_fma_f32 v[40:41], v[40:41], 0.5, v[42:43] op_sel_hi:[1,0,1]
	v_pk_fma_f32 v[38:39], v[38:39], 0.5, v[44:45] op_sel_hi:[1,0,1]
	v_add_f32_e32 v43, v40, v41
	v_add_f32_e32 v42, v38, v39
	v_add_f32_e32 v42, v42, v43
	v_add_f32_e32 v47, v47, v42
	v_mul_f32_e32 v42, v39, v39
	v_mul_f32_e32 v43, v41, v41
	v_fmac_f32_e32 v42, v38, v38
	v_fmac_f32_e32 v43, v40, v40
	v_add_f32_e32 v42, v42, v43
	v_add_f32_e32 v46, v46, v42
	v_sub_f32_e32 v43, v53, v93
	v_sub_f32_e32 v42, v52, v93
	v_sub_f32_e32 v45, v51, v93
	v_sub_f32_e32 v44, v50, v93
	v_pk_mul_f32 v[44:45], v[92:93], v[44:45] op_sel_hi:[0,1]
	v_pk_mul_f32 v[42:43], v[92:93], v[42:43] op_sel_hi:[0,1]
	v_pk_fma_f32 v[42:43], v[56:57], v[42:43], v[60:61]
	v_pk_fma_f32 v[44:45], v[54:55], v[44:45], v[58:59]
	v_pk_mul_f32 v[42:43], v[42:43], s[2:3] op_sel_hi:[1,0]
	v_pk_mul_f32 v[44:45], v[44:45], s[2:3] op_sel_hi:[1,0]
	v_pk_fma_f32 v[36:37], v[36:37], 0.5, v[42:43] op_sel_hi:[1,0,1]
	v_pk_fma_f32 v[34:35], v[34:35], 0.5, v[44:45] op_sel_hi:[1,0,1]
	v_add_f32_e32 v43, v36, v37
	v_add_f32_e32 v42, v34, v35
	v_add_f32_e32 v42, v42, v43
	v_mul_f32_e32 v43, v35, v35
	v_mul_f32_e32 v44, v37, v37
	v_add_f32_e32 v42, v47, v42
	v_fmac_f32_e32 v43, v34, v34
	v_fmac_f32_e32 v44, v36, v36
	s_nop 0
	s_nop 1
	v_bfe_u32 v49, v227, 4, 2
	v_sub_u32_e32 v48, 0, v49
	v_lshlrev_b32_e32 v48, 4, v48
	v_ashrrev_i32_e32 v49, 31, v48
	v_lshl_add_u64 v[48:49], v[94:95], 0, v[48:49]
	v_permlane16_swap_b32_e32 v38, v34
	v_permlane16_swap_b32_e32 v39, v35
	v_permlane16_swap_b32_e32 v40, v36
	v_permlane16_swap_b32_e32 v41, v37
	v_permlane32_swap_b32_e32 v38, v34
	v_permlane32_swap_b32_e32 v39, v35
	v_permlane32_swap_b32_e32 v40, v36
	v_permlane32_swap_b32_e32 v41, v37
	v_mov_b32_e32 v45, v38
	v_mov_b32_e32 v52, v39
	v_mov_b32_e32 v53, v40
	v_mov_b32_e32 v54, v41
	v_bfe_u32 v50, v227, 3, 1
	v_mul_i32_i24_e32 v50, 0xffff8040, v50
	v_ashrrev_i32_e32 v51, 31, v50
	v_lshl_add_u64 v[48:49], v[48:49], 0, v[50:51]
	v_mov_b32_e32 v50, 0x8000
	v_mov_b32_e32 v51, 0
	v_lshl_add_u64 v[50:51], v[48:49], 0, v[50:51]
	v_mov_b32_dpp v38, v34 row_ror:8 row_mask:0xf bank_mask:0xc
	v_mov_b32_dpp v39, v35 row_ror:8 row_mask:0xf bank_mask:0xc
	v_mov_b32_dpp v40, v36 row_ror:8 row_mask:0xf bank_mask:0xc
	v_mov_b32_dpp v41, v37 row_ror:8 row_mask:0xf bank_mask:0xc
	v_mov_b32_dpp v34, v45 row_ror:8 row_mask:0xf bank_mask:0x3
	v_mov_b32_dpp v35, v52 row_ror:8 row_mask:0xf bank_mask:0x3
	v_mov_b32_dpp v36, v53 row_ror:8 row_mask:0xf bank_mask:0x3
	v_mov_b32_dpp v37, v54 row_ror:8 row_mask:0xf bank_mask:0x3
	global_store_dwordx4 v[48:49], v[38:41], off offset:512
	global_store_dwordx4 v[50:51], v[34:37], off offset:512
	s_nop 1
	v_mov_b32_dpp v34, v38 row_ror:8 row_mask:0xf bank_mask:0x3
	v_mov_b32_dpp v35, v39 row_ror:8 row_mask:0xf bank_mask:0x3
	v_mov_b32_dpp v36, v40 row_ror:8 row_mask:0xf bank_mask:0x3
	v_mov_b32_dpp v37, v41 row_ror:8 row_mask:0xf bank_mask:0x3
	v_mov_b32_e32 v38, v45
	v_mov_b32_e32 v39, v52
	v_mov_b32_e32 v40, v53
	v_mov_b32_e32 v41, v54
	s_nop 1
	v_permlane32_swap_b32_e32 v38, v34
	v_permlane32_swap_b32_e32 v39, v35
	v_permlane32_swap_b32_e32 v40, v36
	v_permlane32_swap_b32_e32 v41, v37
	v_permlane16_swap_b32_e32 v38, v34
	v_permlane16_swap_b32_e32 v39, v35
	v_permlane16_swap_b32_e32 v40, v36
	v_permlane16_swap_b32_e32 v41, v37
	v_add_f32_e32 v43, v43, v44
	v_cvt_pk_bf16_f32 v38, v38, v39
	v_cvt_pk_bf16_f32 v39, v40, v41
	v_cvt_pk_bf16_f32 v40, v34, v35
	v_lshl_add_u64 v[34:35], v[78:79], 0, v[0:1]
	v_mov_b32_e32 v0, v42
	v_add_f32_e32 v43, v46, v43
	v_cvt_pk_bf16_f32 v41, v36, v37
	v_permlane16_swap_b32_e32 v42, v0
	global_store_dwordx4 v[34:35], v[38:41], off
	v_add_f32_e32 v34, v42, v0
	v_mov_b32_e32 v0, v43
	s_nop 1
	v_permlane16_swap_b32_e32 v43, v0
	v_add_f32_e32 v35, v43, v0
	v_mov_b32_e32 v36, v34
	v_mov_b32_e32 v37, v35
	s_nop 0
	v_permlane32_swap_b32_e32 v34, v36
	v_permlane32_swap_b32_e32 v35, v37
	s_and_saveexec_b64 s[26:27], s[44:45]
	s_cbranch_execz .LBB0_384
	v_pk_add_f32 v[34:35], v[34:35], v[36:37]
	v_lshl_add_u64 v[36:37], s[30:31], 0, v[86:87]
	v_lshl_add_u64 v[36:37], s[24:25], 2, v[36:37]
	global_store_dwordx2 v[36:37], v[34:35], off
; __device__ __forceinline__ size_t blk_off(int r, int c, int K) { return (size_t)(r >> 8) * 256 * K + (size_t)(c >> 6) * (256 * 64) + (size_t)((r & 255) * 64 + (c & 63)); }
; __device__ __forceinline__ u32x4 pack8(const f32x4 a, const f32x4 b) { u32x4 w; w.x = cvt_pk_bf16(a[0], a[1]); w.y = cvt_pk_bf16(a[2], a[3]); w.z = cvt_pk_bf16(b[0], b[1]); w.w = cvt_pk_bf16(b[2], b[3]); return w; }
;     __device__ __forceinline__ void operator()(const f32x4 (&acc)[2][2][4][2], const pg8::Unit& u, int wr, int wc, int fr, int fq) const {
;     ...
;             for (int m = 0; m < 4; ++m) { const int row = row0 + ai * 128 + m * 16; const float mu = mu4[m], rs = rs4[m];
;                 f32x4 yv[2][2], gq[2][2], bq_[2][2];
; #pragma unroll
;                 for (int bj = 0; bj < 2; ++bj)
; #pragma unroll
;                     for (int n = 0; n < 2; ++n) { yv[bj][n] = *(const f32x4*)(Yin + (size_t)row * D_ + col0 + bj * 128 + 4 * n); gq[bj][n] = *(const f32x4*)(g + col0 + bj * 128 + 4 * n); bq_[bj][n] = *(const f32x4*)(b + col0 + bj * 128 + 4 * n); }
;                 asm volatile("" ::: "memory");
;                 float s1 = 0.f, s2 = 0.f;
; #pragma unroll
;                 for (int bj = 0; bj < 2; ++bj) { float* yp = Y + (size_t)row * D_ + col0 + bj * 128; f32x4 v[2];
; #pragma unroll
;                     for (int n = 0; n < 2; ++n) { v[n] = (((yv[bj][n] - mu) * rs) * gq[bj][n] + bq_[bj][n]) * ALPHA_ + acc[ai][bj][m][n] * sc;
;                         *(f32x4*)(yp + 4 * n) = v[n]; s1 += (v[n][0] + v[n][1]) + (v[n][2] + v[n][3]); s2 += (v[n][0] * v[n][0] + v[n][1] * v[n][1]) + (v[n][2] * v[n][2] + v[n][3] * v[n][3]); }
;                     *(u32x4*)(Yb + blk_off(row, col0 + bj * 128, D_)) = pack8(v[0], v[1]); }
.LBB0_384:
	s_or_b64 exec, exec, s[26:27]
	v_pk_add_f32 v[34:35], v[88:89], v[90:91]
	s_mov_b32 s2, 0x3a800000
	v_pk_mul_f32 v[58:59], v[34:35], s[2:3] op_sel_hi:[1,0]
	s_mov_b32 s2, 0x800000
	v_fma_f32 v0, -v59, v59, v58
	v_max_f32_e32 v0, 0, v0
	v_add_f32_e32 v0, 0x3727c5ac, v0
	v_cmp_gt_f32_e32 vcc, s2, v0
	v_mul_f32_e32 v34, 0x4b800000, v0
	v_lshlrev_b64 v[60:61], 12, v[76:77]
	v_cndmask_b32_e32 v0, v0, v34, vcc
	v_rsq_f32_e32 v0, v0
	s_movk_i32 s2, 0x3bc0
	s_load_dwordx16 s[60:75], s[34:35], 0x38
	v_mul_f32_e32 v34, 0x45800000, v0
	v_cndmask_b32_e32 v58, v0, v34, vcc
	v_lshl_add_u64 v[34:35], s[12:13], 0, v[60:61]
	v_lshl_add_u64 v[38:39], v[34:35], 0, v[152:153]
	global_load_dwordx4 v[62:65], v[38:39], off offset:16
	global_load_dwordx4 v[66:69], v[38:39], off
	global_load_dwordx4 v[70:73], v[154:155], off offset:16
	global_load_dwordx4 v[86:89], v[154:155], off
	global_load_dwordx4 v[90:93], v[156:157], off offset:16
	global_load_dwordx4 v[94:97], v[156:157], off
	global_load_dwordx4 v[34:37], v[38:39], off offset:528
	global_load_dwordx4 v[54:57], v[38:39], off offset:512
	s_nop 0
	global_load_dwordx4 v[38:41], v[154:155], off offset:528
	global_load_dwordx4 v[46:49], v[154:155], off offset:512
	global_load_dwordx4 v[42:45], v[156:157], off offset:528
	global_load_dwordx4 v[50:53], v[156:157], off offset:512
	v_lshlrev_b32_e32 v0, 6, v76
	v_and_or_b32 v0, v0, s2, v194
	s_mov_b32 s2, 0x3fd744fd
	s_waitcnt lgkmcnt(0)
	v_lshl_add_u64 v[60:61], s[74:75], 0, v[60:61]
	v_lshlrev_b32_e32 v0, 1, v0
	v_lshl_add_u64 v[60:61], v[60:61], 0, v[152:153]
	s_waitcnt vmcnt(10)
	v_sub_f32_e32 v69, v69, v59
	v_sub_f32_e32 v68, v68, v59
	v_sub_f32_e32 v67, v67, v59
	v_sub_f32_e32 v66, v66, v59
	v_pk_mul_f32 v[66:67], v[58:59], v[66:67] op_sel_hi:[0,1]
	v_pk_mul_f32 v[68:69], v[58:59], v[68:69] op_sel_hi:[0,1]
	s_waitcnt vmcnt(6)
	v_pk_fma_f32 v[68:69], v[88:89], v[68:69], v[96:97]
	v_pk_fma_f32 v[66:67], v[86:87], v[66:67], v[94:95]
	v_pk_mul_f32 v[68:69], v[68:69], s[2:3] op_sel_hi:[1,0]
	v_pk_mul_f32 v[66:67], v[66:67], s[2:3] op_sel_hi:[1,0]
	v_pk_fma_f32 v[68:69], v[32:33], 0.5, v[68:69] op_sel_hi:[1,0,1]
	v_pk_fma_f32 v[66:67], v[30:31], 0.5, v[66:67] op_sel_hi:[1,0,1]
	v_add_f32_e32 v31, v68, v69
	v_add_f32_e32 v30, v66, v67
	v_add_f32_e32 v30, v30, v31
	v_add_f32_e32 v86, 0, v30
	v_mul_f32_e32 v30, v67, v67
	v_mul_f32_e32 v31, v69, v69
	v_fmac_f32_e32 v30, v66, v66
	v_fmac_f32_e32 v31, v68, v68
	v_add_f32_e32 v87, v30, v31
	v_sub_f32_e32 v31, v65, v59
	v_sub_f32_e32 v30, v64, v59
	v_sub_f32_e32 v33, v63, v59
	v_sub_f32_e32 v32, v62, v59
	v_pk_mul_f32 v[32:33], v[58:59], v[32:33] op_sel_hi:[0,1]
	v_pk_mul_f32 v[30:31], v[58:59], v[30:31] op_sel_hi:[0,1]
	v_pk_fma_f32 v[30:31], v[72:73], v[30:31], v[92:93]
	v_pk_fma_f32 v[32:33], v[70:71], v[32:33], v[90:91]
	v_pk_mul_f32 v[30:31], v[30:31], s[2:3] op_sel_hi:[1,0]
	v_pk_mul_f32 v[32:33], v[32:33], s[2:3] op_sel_hi:[1,0]
	v_pk_fma_f32 v[64:65], v[28:29], 0.5, v[30:31] op_sel_hi:[1,0,1]
	v_pk_fma_f32 v[62:63], v[26:27], 0.5, v[32:33] op_sel_hi:[1,0,1]
	v_add_f32_e32 v27, v64, v65
	v_add_f32_e32 v26, v62, v63
	v_add_f32_e32 v26, v26, v27
	v_add_f32_e32 v31, v86, v26
	v_mul_f32_e32 v26, v63, v63
	v_mul_f32_e32 v27, v65, v65
	v_fmac_f32_e32 v26, v62, v62
	v_fmac_f32_e32 v27, v64, v64
	v_add_f32_e32 v26, v26, v27
	v_add_f32_e32 v30, v87, v26
	v_cvt_pk_bf16_f32 v26, v66, v67
	v_cvt_pk_bf16_f32 v27, v68, v69
	v_cvt_pk_bf16_f32 v28, v62, v63
	v_cvt_pk_bf16_f32 v29, v64, v65
	v_lshl_add_u64 v[32:33], v[80:81], 0, v[0:1]
	s_nop 0
	s_nop 1
	v_bfe_u32 v71, v227, 4, 2
	v_sub_u32_e32 v70, 0, v71
	v_lshlrev_b32_e32 v70, 4, v70
	v_ashrrev_i32_e32 v71, 31, v70
	v_lshl_add_u64 v[70:71], v[60:61], 0, v[70:71]
	v_permlane16_swap_b32_e32 v66, v62
	v_permlane16_swap_b32_e32 v67, v63
	v_permlane16_swap_b32_e32 v68, v64
	v_permlane16_swap_b32_e32 v69, v65
	v_permlane32_swap_b32_e32 v66, v62
	v_permlane32_swap_b32_e32 v67, v63
	v_permlane32_swap_b32_e32 v68, v64
	v_permlane32_swap_b32_e32 v69, v65
	v_mov_b32_e32 v86, v66
	v_mov_b32_e32 v87, v67
	v_mov_b32_e32 v88, v68
	v_mov_b32_e32 v89, v69
	v_bfe_u32 v72, v227, 3, 1
	v_mul_i32_i24_e32 v72, 0xffff8040, v72
	v_ashrrev_i32_e32 v73, 31, v72
	v_lshl_add_u64 v[70:71], v[70:71], 0, v[72:73]
	v_mov_b32_e32 v72, 0x8000
	v_mov_b32_e32 v73, 0
	v_lshl_add_u64 v[72:73], v[70:71], 0, v[72:73]
	v_mov_b32_dpp v66, v62 row_ror:8 row_mask:0xf bank_mask:0xc
	v_mov_b32_dpp v67, v63 row_ror:8 row_mask:0xf bank_mask:0xc
	v_mov_b32_dpp v68, v64 row_ror:8 row_mask:0xf bank_mask:0xc
	v_mov_b32_dpp v69, v65 row_ror:8 row_mask:0xf bank_mask:0xc
	v_mov_b32_dpp v62, v86 row_ror:8 row_mask:0xf bank_mask:0x3
	v_mov_b32_dpp v63, v87 row_ror:8 row_mask:0xf bank_mask:0x3
	v_mov_b32_dpp v64, v88 row_ror:8 row_mask:0xf bank_mask:0x3
	v_mov_b32_dpp v65, v89 row_ror:8 row_mask:0xf bank_mask:0x3
	global_store_dwordx4 v[70:71], v[66:69], off
	global_store_dwordx4 v[72:73], v[62:65], off
	s_nop 1
	global_store_dwordx4 v[32:33], v[26:29], off
	s_waitcnt vmcnt(7)
; __device__ __forceinline__ float xsum16(float v) { const auto r = __builtin_amdgcn_permlane16_swap(__float_as_uint(v), __float_as_uint(v), false, false); return __uint_as_float(r[0]) + __uint_as_float(r[1]); }
; __device__ __forceinline__ float xsum32(float v) { const auto r = __builtin_amdgcn_permlane32_swap(__float_as_uint(v), __float_as_uint(v), false, false); return __uint_as_float(r[0]) + __uint_as_float(r[1]); }
; __device__ __forceinline__ size_t blk_off(int r, int c, int K) { return (size_t)(r >> 8) * 256 * K + (size_t)(c >> 6) * (256 * 64) + (size_t)((r & 255) * 64 + (c & 63)); }
; __device__ __forceinline__ u32x4 pack8(const f32x4 a, const f32x4 b) { u32x4 w; w.x = cvt_pk_bf16(a[0], a[1]); w.y = cvt_pk_bf16(a[2], a[3]); w.z = cvt_pk_bf16(b[0], b[1]); w.w = cvt_pk_bf16(b[2], b[3]); return w; }
;     __device__ __forceinline__ void operator()(const f32x4 (&acc)[2][2][4][2], const pg8::Unit& u, int wr, int wc, int fr, int fq) const {
;     ...
;                 for (int bj = 0; bj < 2; ++bj) { float* yp = Y + (size_t)row * D_ + col0 + bj * 128; f32x4 v[2];
; #pragma unroll
;                     for (int n = 0; n < 2; ++n) { v[n] = (((yv[bj][n] - mu) * rs) * gq[bj][n] + bq_[bj][n]) * ALPHA_ + acc[ai][bj][m][n] * sc;
;                         *(f32x4*)(yp + 4 * n) = v[n]; s1 += (v[n][0] + v[n][1]) + (v[n][2] + v[n][3]); s2 += (v[n][0] * v[n][0] + v[n][1] * v[n][1]) + (v[n][2] * v[n][2] + v[n][3] * v[n][3]); }
;                     *(u32x4*)(Yb + blk_off(row, col0 + bj * 128, D_)) = pack8(v[0], v[1]); }
;                 s1 = xsum32(xsum16(s1)); s2 = xsum32(xsum16(s2));
;                 if (fq == 0) *(f32x2*)(stn + (size_t)row * 32 + (u.pn * 4 + wc) * 2) = (f32x2){s1, s2}; asm volatile("" ::: "memory"); } }
	s_nop 0
	v_sub_f32_e32 v27, v57, v59
	v_sub_f32_e32 v26, v56, v59
	v_sub_f32_e32 v29, v55, v59
	v_sub_f32_e32 v28, v54, v59
	v_pk_mul_f32 v[28:29], v[58:59], v[28:29] op_sel_hi:[0,1]
	v_pk_mul_f32 v[26:27], v[58:59], v[26:27] op_sel_hi:[0,1]
	s_waitcnt vmcnt(3)
	v_pk_fma_f32 v[26:27], v[48:49], v[26:27], v[52:53]
	v_pk_fma_f32 v[28:29], v[46:47], v[28:29], v[50:51]
	v_pk_mul_f32 v[26:27], v[26:27], s[2:3] op_sel_hi:[1,0]
	v_pk_mul_f32 v[28:29], v[28:29], s[2:3] op_sel_hi:[1,0]
	v_pk_fma_f32 v[24:25], v[24:25], 0.5, v[26:27] op_sel_hi:[1,0,1]
	v_pk_fma_f32 v[22:23], v[22:23], 0.5, v[28:29] op_sel_hi:[1,0,1]
	v_add_f32_e32 v27, v24, v25
	v_add_f32_e32 v26, v22, v23
	v_add_f32_e32 v26, v26, v27
	v_add_f32_e32 v31, v31, v26
	v_mul_f32_e32 v26, v23, v23
	v_mul_f32_e32 v27, v25, v25
	v_fmac_f32_e32 v26, v22, v22
	v_fmac_f32_e32 v27, v24, v24
	v_add_f32_e32 v26, v26, v27
	v_add_f32_e32 v30, v30, v26
	v_sub_f32_e32 v27, v37, v59
	v_sub_f32_e32 v26, v36, v59
	v_sub_f32_e32 v29, v35, v59
	v_sub_f32_e32 v28, v34, v59
	v_pk_mul_f32 v[28:29], v[58:59], v[28:29] op_sel_hi:[0,1]
	v_pk_mul_f32 v[26:27], v[58:59], v[26:27] op_sel_hi:[0,1]
	v_pk_fma_f32 v[26:27], v[40:41], v[26:27], v[44:45]
	v_pk_fma_f32 v[28:29], v[38:39], v[28:29], v[42:43]
	v_pk_mul_f32 v[26:27], v[26:27], s[2:3] op_sel_hi:[1,0]
	v_pk_mul_f32 v[28:29], v[28:29], s[2:3] op_sel_hi:[1,0]
	v_pk_fma_f32 v[20:21], v[20:21], 0.5, v[26:27] op_sel_hi:[1,0,1]
	v_pk_fma_f32 v[18:19], v[18:19], 0.5, v[28:29] op_sel_hi:[1,0,1]
	v_add_f32_e32 v27, v20, v21
	v_add_f32_e32 v26, v18, v19
	v_add_f32_e32 v26, v26, v27
	v_mul_f32_e32 v27, v19, v19
	v_mul_f32_e32 v28, v21, v21
	v_add_f32_e32 v26, v31, v26
	v_fmac_f32_e32 v27, v18, v18
	v_fmac_f32_e32 v28, v20, v20
	s_nop 0
	s_nop 1
	v_bfe_u32 v33, v227, 4, 2
	v_sub_u32_e32 v32, 0, v33
	v_lshlrev_b32_e32 v32, 4, v32
	v_ashrrev_i32_e32 v33, 31, v32
	v_lshl_add_u64 v[32:33], v[60:61], 0, v[32:33]
	v_permlane16_swap_b32_e32 v22, v18
	v_permlane16_swap_b32_e32 v23, v19
	v_permlane16_swap_b32_e32 v24, v20
	v_permlane16_swap_b32_e32 v25, v21
	v_permlane32_swap_b32_e32 v22, v18
	v_permlane32_swap_b32_e32 v23, v19
	v_permlane32_swap_b32_e32 v24, v20
	v_permlane32_swap_b32_e32 v25, v21
	v_mov_b32_e32 v29, v22
	v_mov_b32_e32 v36, v23
	v_mov_b32_e32 v37, v24
	v_mov_b32_e32 v38, v25
	v_bfe_u32 v34, v227, 3, 1
	v_mul_i32_i24_e32 v34, 0xffff8040, v34
	v_ashrrev_i32_e32 v35, 31, v34
	v_lshl_add_u64 v[32:33], v[32:33], 0, v[34:35]
	v_mov_b32_e32 v34, 0x8000
	v_mov_b32_e32 v35, 0
	v_lshl_add_u64 v[34:35], v[32:33], 0, v[34:35]
	v_mov_b32_dpp v22, v18 row_ror:8 row_mask:0xf bank_mask:0xc
	v_mov_b32_dpp v23, v19 row_ror:8 row_mask:0xf bank_mask:0xc
	v_mov_b32_dpp v24, v20 row_ror:8 row_mask:0xf bank_mask:0xc
	v_mov_b32_dpp v25, v21 row_ror:8 row_mask:0xf bank_mask:0xc
	v_mov_b32_dpp v18, v29 row_ror:8 row_mask:0xf bank_mask:0x3
	v_mov_b32_dpp v19, v36 row_ror:8 row_mask:0xf bank_mask:0x3
	v_mov_b32_dpp v20, v37 row_ror:8 row_mask:0xf bank_mask:0x3
	v_mov_b32_dpp v21, v38 row_ror:8 row_mask:0xf bank_mask:0x3
	global_store_dwordx4 v[32:33], v[22:25], off offset:512
	global_store_dwordx4 v[34:35], v[18:21], off offset:512
	s_nop 1
	v_mov_b32_dpp v18, v22 row_ror:8 row_mask:0xf bank_mask:0x3
	v_mov_b32_dpp v19, v23 row_ror:8 row_mask:0xf bank_mask:0x3
	v_mov_b32_dpp v20, v24 row_ror:8 row_mask:0xf bank_mask:0x3
	v_mov_b32_dpp v21, v25 row_ror:8 row_mask:0xf bank_mask:0x3
	v_mov_b32_e32 v22, v29
	v_mov_b32_e32 v23, v36
	v_mov_b32_e32 v24, v37
	v_mov_b32_e32 v25, v38
	s_nop 1
	v_permlane32_swap_b32_e32 v22, v18
	v_permlane32_swap_b32_e32 v23, v19
	v_permlane32_swap_b32_e32 v24, v20
	v_permlane32_swap_b32_e32 v25, v21
	v_permlane16_swap_b32_e32 v22, v18
	v_permlane16_swap_b32_e32 v23, v19
	v_permlane16_swap_b32_e32 v24, v20
	v_permlane16_swap_b32_e32 v25, v21
	v_add_f32_e32 v27, v27, v28
	v_cvt_pk_bf16_f32 v22, v22, v23
	v_cvt_pk_bf16_f32 v23, v24, v25
	v_cvt_pk_bf16_f32 v24, v18, v19
	v_lshl_add_u64 v[18:19], v[78:79], 0, v[0:1]
	v_mov_b32_e32 v0, v26
	v_add_f32_e32 v27, v30, v27
	v_cvt_pk_bf16_f32 v25, v20, v21
	v_permlane16_swap_b32_e32 v26, v0
	global_store_dwordx4 v[18:19], v[22:25], off
	v_add_f32_e32 v18, v26, v0
	v_mov_b32_e32 v0, v27
	s_nop 1
	v_permlane16_swap_b32_e32 v27, v0
	v_add_f32_e32 v19, v27, v0
	v_mov_b32_e32 v20, v18
	v_mov_b32_e32 v21, v19
	s_nop 0
	v_permlane32_swap_b32_e32 v18, v20
	v_permlane32_swap_b32_e32 v19, v21
	s_and_saveexec_b64 s[26:27], s[44:45]
	s_cbranch_execz .LBB0_386
	v_pk_add_f32 v[18:19], v[18:19], v[20:21]
	v_lshlrev_b64 v[20:21], 7, v[76:77]
	v_lshl_add_u64 v[20:21], s[30:31], 0, v[20:21]
	v_lshl_add_u64 v[20:21], s[24:25], 2, v[20:21]
	global_store_dwordx2 v[20:21], v[18:19], off

; __device__ __forceinline__ size_t blk_off(int r, int c, int K) { return (size_t)(r >> 8) * 256 * K + (size_t)(c >> 6) * (256 * 64) + (size_t)((r & 255) * 64 + (c & 63)); }
; __device__ __forceinline__ u32x4 pack8(const f32x4 a, const f32x4 b) { u32x4 w; w.x = cvt_pk_bf16(a[0], a[1]); w.y = cvt_pk_bf16(a[2], a[3]); w.z = cvt_pk_bf16(b[0], b[1]); w.w = cvt_pk_bf16(b[2], b[3]); return w; }
;     __device__ __forceinline__ void operator()(const f32x4 (&acc)[2][2][4][2], const pg8::Unit& u, int wr, int wc, int fr, int fq) const {
;     ...
;             for (int m = 0; m < 4; ++m) { const int row = row0 + ai * 128 + m * 16; const float mu = mu4[m], rs = rs4[m];
;                 f32x4 yv[2][2], gq[2][2], bq_[2][2];
; #pragma unroll
;                 for (int bj = 0; bj < 2; ++bj)
; #pragma unroll
;                     for (int n = 0; n < 2; ++n) { yv[bj][n] = *(const f32x4*)(Yin + (size_t)row * D_ + col0 + bj * 128 + 4 * n); gq[bj][n] = *(const f32x4*)(g + col0 + bj * 128 + 4 * n); bq_[bj][n] = *(const f32x4*)(b + col0 + bj * 128 + 4 * n); }
;                 asm volatile("" ::: "memory");
;                 float s1 = 0.f, s2 = 0.f;
; #pragma unroll
;                 for (int bj = 0; bj < 2; ++bj) { float* yp = Y + (size_t)row * D_ + col0 + bj * 128; f32x4 v[2];
; #pragma unroll
;                     for (int n = 0; n < 2; ++n) { v[n] = (((yv[bj][n] - mu) * rs) * gq[bj][n] + bq_[bj][n]) * ALPHA_ + acc[ai][bj][m][n] * sc;
;                         *(f32x4*)(yp + 4 * n) = v[n]; s1 += (v[n][0] + v[n][1]) + (v[n][2] + v[n][3]); s2 += (v[n][0] * v[n][0] + v[n][1] * v[n][1]) + (v[n][2] * v[n][2] + v[n][3] * v[n][3]); }
;                     *(u32x4*)(Yb + blk_off(row, col0 + bj * 128, D_)) = pack8(v[0], v[1]); }
.LBB0_1545:
	s_or_b64 exec, exec, s[24:25]
	v_pk_add_f32 v[50:51], v[112:113], v[114:115]
	s_mov_b32 s2, 0x3a800000
	v_pk_mul_f32 v[78:79], v[50:51], s[2:3] op_sel_hi:[1,0]
	s_mov_b32 s1, 0x800000
	v_fma_f32 v0, -v79, v79, v78
	v_max_f32_e32 v0, 0, v0
	v_add_f32_e32 v0, 0x3727c5ac, v0
	v_cmp_gt_f32_e32 vcc, s1, v0
	v_mul_f32_e32 v50, 0x4b800000, v0
	s_load_dwordx16 s[64:79], s[34:35], 0x38
	v_cndmask_b32_e32 v0, v0, v50, vcc
	v_rsq_f32_e32 v0, v0
	s_mov_b32 s2, 0x3fd744fd
	s_movk_i32 s1, 0x37c0
	v_mul_f32_e32 v50, 0x45800000, v0
	v_cndmask_b32_e32 v78, v0, v50, vcc
	v_lshlrev_b64 v[50:51], 12, v[108:109]
	s_waitcnt lgkmcnt(0)
	v_lshl_add_u64 v[50:51], s[78:79], 0, v[50:51]
	v_lshl_add_u64 v[80:81], v[152:153], 2, v[50:51]
	global_load_dwordx4 v[82:85], v[80:81], off offset:16
	global_load_dwordx4 v[86:89], v[80:81], off
	global_load_dwordx4 v[90:93], v[156:157], off offset:16
	global_load_dwordx4 v[110:113], v[156:157], off
	global_load_dwordx4 v[114:117], v[154:155], off offset:16
	global_load_dwordx4 v[118:121], v[154:155], off
	global_load_dwordx4 v[50:53], v[80:81], off offset:528
	global_load_dwordx4 v[70:73], v[80:81], off offset:512
	global_load_dwordx4 v[54:57], v[156:157], off offset:528
	global_load_dwordx4 v[62:65], v[156:157], off offset:512
	global_load_dwordx4 v[58:61], v[154:155], off offset:528
	global_load_dwordx4 v[66:69], v[154:155], off offset:512
	v_lshlrev_b32_e32 v0, 6, v108
	v_and_or_b32 v0, v0, s1, v196
	v_lshlrev_b32_e32 v0, 1, v0
	s_waitcnt vmcnt(10)
	v_sub_f32_e32 v87, v87, v79
	v_sub_f32_e32 v86, v86, v79
	v_sub_f32_e32 v89, v89, v79
	v_sub_f32_e32 v88, v88, v79
	v_pk_mul_f32 v[88:89], v[78:79], v[88:89] op_sel_hi:[0,1]
	v_pk_mul_f32 v[86:87], v[78:79], v[86:87] op_sel_hi:[0,1]
	s_waitcnt vmcnt(6)
	v_pk_fma_f32 v[86:87], v[110:111], v[86:87], v[118:119]
	v_pk_fma_f32 v[88:89], v[112:113], v[88:89], v[120:121]
	v_pk_fma_f32 v[86:87], v[86:87], s[2:3], v[46:47] op_sel_hi:[1,0,1]
	v_pk_fma_f32 v[88:89], v[88:89], s[2:3], v[48:49] op_sel_hi:[1,0,1]
	v_add_f32_e32 v46, v86, v87
	v_add_f32_e32 v47, v88, v89
	v_add_f32_e32 v46, v46, v47
	v_add_f32_e32 v108, 0, v46
	v_mul_f32_e32 v46, v87, v87
	v_mul_f32_e32 v47, v89, v89
	v_fmac_f32_e32 v46, v86, v86
	v_fmac_f32_e32 v47, v88, v88
	v_add_f32_e32 v109, v46, v47
	v_sub_f32_e32 v47, v83, v79
	v_sub_f32_e32 v46, v82, v79
	v_sub_f32_e32 v49, v85, v79
	v_sub_f32_e32 v48, v84, v79
	v_pk_mul_f32 v[48:49], v[78:79], v[48:49] op_sel_hi:[0,1]
	v_pk_mul_f32 v[46:47], v[78:79], v[46:47] op_sel_hi:[0,1]
	v_pk_fma_f32 v[46:47], v[90:91], v[46:47], v[114:115]
	v_pk_fma_f32 v[48:49], v[92:93], v[48:49], v[116:117]
	v_pk_fma_f32 v[82:83], v[46:47], s[2:3], v[42:43] op_sel_hi:[1,0,1]
	v_pk_fma_f32 v[84:85], v[48:49], s[2:3], v[44:45] op_sel_hi:[1,0,1]
	v_add_f32_e32 v42, v82, v83
	v_add_f32_e32 v43, v84, v85
	v_add_f32_e32 v42, v42, v43
	v_add_f32_e32 v47, v108, v42
	v_mul_f32_e32 v42, v83, v83
	v_mul_f32_e32 v43, v85, v85
	v_fmac_f32_e32 v42, v82, v82
	v_fmac_f32_e32 v43, v84, v84
	v_add_f32_e32 v42, v42, v43
	v_add_f32_e32 v46, v109, v42
	v_cvt_pk_bf16_f32 v42, v86, v87
	v_cvt_pk_bf16_f32 v43, v88, v89
	v_cvt_pk_bf16_f32 v44, v82, v83
	v_cvt_pk_bf16_f32 v45, v84, v85
	v_lshl_add_u64 v[48:49], v[76:77], 0, v[0:1]
	s_nop 0
	s_nop 1
	v_bfe_u32 v91, v227, 4, 2
	v_sub_u32_e32 v90, 0, v91
	v_lshlrev_b32_e32 v90, 4, v90
	v_ashrrev_i32_e32 v91, 31, v90
	v_lshl_add_u64 v[90:91], v[80:81], 0, v[90:91]
	v_permlane16_swap_b32_e32 v86, v82
	v_permlane16_swap_b32_e32 v87, v83
	v_permlane16_swap_b32_e32 v88, v84
	v_permlane16_swap_b32_e32 v89, v85
	v_permlane32_swap_b32_e32 v86, v82
	v_permlane32_swap_b32_e32 v87, v83
	v_permlane32_swap_b32_e32 v88, v84
	v_permlane32_swap_b32_e32 v89, v85
	v_mov_b32_e32 v108, v86
	v_mov_b32_e32 v109, v87
	v_mov_b32_e32 v110, v88
	v_mov_b32_e32 v111, v89
	v_bfe_u32 v92, v227, 3, 1
	v_mul_i32_i24_e32 v92, 0xffff8040, v92
	v_ashrrev_i32_e32 v93, 31, v92
	v_lshl_add_u64 v[90:91], v[90:91], 0, v[92:93]
	v_mov_b32_e32 v92, 0x8000
	v_mov_b32_e32 v93, 0
	v_lshl_add_u64 v[92:93], v[90:91], 0, v[92:93]
	v_mov_b32_dpp v86, v82 row_ror:8 row_mask:0xf bank_mask:0xc
	v_mov_b32_dpp v87, v83 row_ror:8 row_mask:0xf bank_mask:0xc
	v_mov_b32_dpp v88, v84 row_ror:8 row_mask:0xf bank_mask:0xc
	v_mov_b32_dpp v89, v85 row_ror:8 row_mask:0xf bank_mask:0xc
	v_mov_b32_dpp v82, v108 row_ror:8 row_mask:0xf bank_mask:0x3
	v_mov_b32_dpp v83, v109 row_ror:8 row_mask:0xf bank_mask:0x3
	v_mov_b32_dpp v84, v110 row_ror:8 row_mask:0xf bank_mask:0x3
	v_mov_b32_dpp v85, v111 row_ror:8 row_mask:0xf bank_mask:0x3
	global_store_dwordx4 v[90:91], v[86:89], off
	global_store_dwordx4 v[92:93], v[82:85], off
	s_nop 1
	global_store_dwordx4 v[48:49], v[42:45], off
	s_waitcnt vmcnt(7)
	s_nop 0
	v_sub_f32_e32 v43, v71, v79
	v_sub_f32_e32 v42, v70, v79
	v_sub_f32_e32 v45, v73, v79
	v_sub_f32_e32 v44, v72, v79
	v_pk_mul_f32 v[44:45], v[78:79], v[44:45] op_sel_hi:[0,1]
	v_pk_mul_f32 v[42:43], v[78:79], v[42:43] op_sel_hi:[0,1]
	s_waitcnt vmcnt(3)
; __device__ __forceinline__ float xsum16(float v) { const auto r = __builtin_amdgcn_permlane16_swap(__float_as_uint(v), __float_as_uint(v), false, false); return __uint_as_float(r[0]) + __uint_as_float(r[1]); }
; __device__ __forceinline__ float xsum32(float v) { const auto r = __builtin_amdgcn_permlane32_swap(__float_as_uint(v), __float_as_uint(v), false, false); return __uint_as_float(r[0]) + __uint_as_float(r[1]); }
; __device__ __forceinline__ size_t blk_off(int r, int c, int K) { return (size_t)(r >> 8) * 256 * K + (size_t)(c >> 6) * (256 * 64) + (size_t)((r & 255) * 64 + (c & 63)); }
; __device__ __forceinline__ u32x4 pack8(const f32x4 a, const f32x4 b) { u32x4 w; w.x = cvt_pk_bf16(a[0], a[1]); w.y = cvt_pk_bf16(a[2], a[3]); w.z = cvt_pk_bf16(b[0], b[1]); w.w = cvt_pk_bf16(b[2], b[3]); return w; }
;     __device__ __forceinline__ void operator()(const f32x4 (&acc)[2][2][4][2], const pg8::Unit& u, int wr, int wc, int fr, int fq) const {
;     ...
;                 for (int bj = 0; bj < 2; ++bj) { float* yp = Y + (size_t)row * D_ + col0 + bj * 128; f32x4 v[2];
; #pragma unroll
;                     for (int n = 0; n < 2; ++n) { v[n] = (((yv[bj][n] - mu) * rs) * gq[bj][n] + bq_[bj][n]) * ALPHA_ + acc[ai][bj][m][n] * sc;
;                         *(f32x4*)(yp + 4 * n) = v[n]; s1 += (v[n][0] + v[n][1]) + (v[n][2] + v[n][3]); s2 += (v[n][0] * v[n][0] + v[n][1] * v[n][1]) + (v[n][2] * v[n][2] + v[n][3] * v[n][3]); }
;                     *(u32x4*)(Yb + blk_off(row, col0 + bj * 128, D_)) = pack8(v[0], v[1]); }
;                 s1 = xsum32(xsum16(s1)); s2 = xsum32(xsum16(s2));
;                 if (fq == 0) *(f32x2*)(stn + (size_t)row * 32 + (u.pn * 4 + wc) * 2) = (f32x2){s1, s2}; asm volatile("" ::: "memory"); } }
	v_pk_fma_f32 v[42:43], v[62:63], v[42:43], v[66:67]
	v_pk_fma_f32 v[44:45], v[64:65], v[44:45], v[68:69]
	v_pk_fma_f32 v[38:39], v[42:43], s[2:3], v[38:39] op_sel_hi:[1,0,1]
	v_pk_fma_f32 v[40:41], v[44:45], s[2:3], v[40:41] op_sel_hi:[1,0,1]
	v_add_f32_e32 v42, v38, v39
	v_add_f32_e32 v43, v40, v41
	v_add_f32_e32 v42, v42, v43
	v_add_f32_e32 v47, v47, v42
	v_mul_f32_e32 v42, v39, v39
	v_mul_f32_e32 v43, v41, v41
	v_fmac_f32_e32 v42, v38, v38
	v_fmac_f32_e32 v43, v40, v40
	v_add_f32_e32 v42, v42, v43
	v_add_f32_e32 v46, v46, v42
	v_sub_f32_e32 v43, v51, v79
	v_sub_f32_e32 v42, v50, v79
	v_sub_f32_e32 v45, v53, v79
	v_sub_f32_e32 v44, v52, v79
	v_pk_mul_f32 v[44:45], v[78:79], v[44:45] op_sel_hi:[0,1]
	v_pk_mul_f32 v[42:43], v[78:79], v[42:43] op_sel_hi:[0,1]
	v_pk_fma_f32 v[42:43], v[54:55], v[42:43], v[58:59]
	v_pk_fma_f32 v[44:45], v[56:57], v[44:45], v[60:61]
	v_pk_fma_f32 v[34:35], v[42:43], s[2:3], v[34:35] op_sel_hi:[1,0,1]
	v_pk_fma_f32 v[36:37], v[44:45], s[2:3], v[36:37] op_sel_hi:[1,0,1]
	v_add_f32_e32 v42, v34, v35
	v_add_f32_e32 v43, v36, v37
	v_add_f32_e32 v42, v42, v43
	v_mul_f32_e32 v43, v35, v35
	v_mul_f32_e32 v44, v37, v37
	v_add_f32_e32 v42, v47, v42
	v_fmac_f32_e32 v43, v34, v34
	v_fmac_f32_e32 v44, v36, v36
	s_nop 0
	s_nop 1
	v_bfe_u32 v49, v227, 4, 2
	v_sub_u32_e32 v48, 0, v49
	v_lshlrev_b32_e32 v48, 4, v48
	v_ashrrev_i32_e32 v49, 31, v48
	v_lshl_add_u64 v[48:49], v[80:81], 0, v[48:49]
	v_permlane16_swap_b32_e32 v38, v34
	v_permlane16_swap_b32_e32 v39, v35
	v_permlane16_swap_b32_e32 v40, v36
	v_permlane16_swap_b32_e32 v41, v37
	v_permlane32_swap_b32_e32 v38, v34
	v_permlane32_swap_b32_e32 v39, v35
	v_permlane32_swap_b32_e32 v40, v36
	v_permlane32_swap_b32_e32 v41, v37
	v_mov_b32_e32 v45, v38
	v_mov_b32_e32 v52, v39
	v_mov_b32_e32 v53, v40
	v_mov_b32_e32 v54, v41
	v_bfe_u32 v50, v227, 3, 1
	v_mul_i32_i24_e32 v50, 0xffff8040, v50
	v_ashrrev_i32_e32 v51, 31, v50
	v_lshl_add_u64 v[48:49], v[48:49], 0, v[50:51]
	v_mov_b32_e32 v50, 0x8000
	v_mov_b32_e32 v51, 0
	v_lshl_add_u64 v[50:51], v[48:49], 0, v[50:51]
	v_mov_b32_dpp v38, v34 row_ror:8 row_mask:0xf bank_mask:0xc
	v_mov_b32_dpp v39, v35 row_ror:8 row_mask:0xf bank_mask:0xc
	v_mov_b32_dpp v40, v36 row_ror:8 row_mask:0xf bank_mask:0xc
	v_mov_b32_dpp v41, v37 row_ror:8 row_mask:0xf bank_mask:0xc
	v_mov_b32_dpp v34, v45 row_ror:8 row_mask:0xf bank_mask:0x3
	v_mov_b32_dpp v35, v52 row_ror:8 row_mask:0xf bank_mask:0x3
	v_mov_b32_dpp v36, v53 row_ror:8 row_mask:0xf bank_mask:0x3
	v_mov_b32_dpp v37, v54 row_ror:8 row_mask:0xf bank_mask:0x3
	global_store_dwordx4 v[48:49], v[38:41], off offset:512
	global_store_dwordx4 v[50:51], v[34:37], off offset:512
	s_nop 1
	v_mov_b32_dpp v34, v38 row_ror:8 row_mask:0xf bank_mask:0x3
	v_mov_b32_dpp v35, v39 row_ror:8 row_mask:0xf bank_mask:0x3
	v_mov_b32_dpp v36, v40 row_ror:8 row_mask:0xf bank_mask:0x3
	v_mov_b32_dpp v37, v41 row_ror:8 row_mask:0xf bank_mask:0x3
	v_mov_b32_e32 v38, v45
	v_mov_b32_e32 v39, v52
	v_mov_b32_e32 v40, v53
	v_mov_b32_e32 v41, v54
	s_nop 1
	v_permlane32_swap_b32_e32 v38, v34
	v_permlane32_swap_b32_e32 v39, v35
	v_permlane32_swap_b32_e32 v40, v36
	v_permlane32_swap_b32_e32 v41, v37
	v_permlane16_swap_b32_e32 v38, v34
	v_permlane16_swap_b32_e32 v39, v35
	v_permlane16_swap_b32_e32 v40, v36
	v_permlane16_swap_b32_e32 v41, v37
	v_add_f32_e32 v43, v43, v44
	v_cvt_pk_bf16_f32 v38, v38, v39
	v_cvt_pk_bf16_f32 v39, v40, v41
	v_cvt_pk_bf16_f32 v40, v34, v35
	v_lshl_add_u64 v[34:35], v[74:75], 0, v[0:1]
	v_mov_b32_e32 v0, v42
	v_add_f32_e32 v43, v46, v43
	v_cvt_pk_bf16_f32 v41, v36, v37
	v_permlane16_swap_b32_e32 v42, v0
	global_store_dwordx4 v[34:35], v[38:41], off
	v_add_f32_e32 v34, v42, v0
	v_mov_b32_e32 v0, v43
	s_nop 1
	v_permlane16_swap_b32_e32 v43, v0
	v_add_f32_e32 v35, v43, v0
	v_mov_b32_e32 v36, v34
	v_mov_b32_e32 v37, v35
	s_nop 0
	v_permlane32_swap_b32_e32 v34, v36
	v_permlane32_swap_b32_e32 v35, v37
	s_and_saveexec_b64 s[24:25], s[44:45]
	s_cbranch_execz .LBB0_1547
	v_pk_add_f32 v[34:35], v[34:35], v[36:37]
	v_lshl_add_u64 v[36:37], s[6:7], 0, v[102:103]
	v_lshl_add_u64 v[36:37], s[52:53], 2, v[36:37]
	global_store_dwordx2 v[36:37], v[34:35], off
.LBB0_1547:
	s_or_b64 exec, exec, s[24:25]
	v_pk_add_f32 v[34:35], v[104:105], v[106:107]
	s_mov_b32 s2, 0x3a800000
	v_pk_mul_f32 v[58:59], v[34:35], s[2:3] op_sel_hi:[1,0]
	s_mov_b32 s1, 0x800000
	v_fma_f32 v0, -v59, v59, v58
	v_max_f32_e32 v0, 0, v0
	v_add_f32_e32 v0, 0x3727c5ac, v0
	v_cmp_gt_f32_e32 vcc, s1, v0
	v_mul_f32_e32 v34, 0x4b800000, v0
	s_load_dwordx16 s[64:79], s[34:35], 0x38
	v_cndmask_b32_e32 v0, v0, v34, vcc
	v_rsq_f32_e32 v0, v0
	s_mov_b32 s2, 0x3fd744fd
	s_movk_i32 s1, 0x3bc0
	v_mul_f32_e32 v34, 0x45800000, v0
	v_cndmask_b32_e32 v58, v0, v34, vcc
	v_lshlrev_b64 v[34:35], 12, v[96:97]
	s_waitcnt lgkmcnt(0)
	v_lshl_add_u64 v[34:35], s[78:79], 0, v[34:35]
	v_lshl_add_u64 v[60:61], v[152:153], 2, v[34:35]
	global_load_dwordx4 v[62:65], v[60:61], off offset:16
	global_load_dwordx4 v[66:69], v[60:61], off
	global_load_dwordx4 v[70:73], v[156:157], off offset:16
	global_load_dwordx4 v[78:81], v[156:157], off
	global_load_dwordx4 v[82:85], v[154:155], off offset:16
	global_load_dwordx4 v[86:89], v[154:155], off
	global_load_dwordx4 v[34:37], v[60:61], off offset:528
	global_load_dwordx4 v[54:57], v[60:61], off offset:512
	global_load_dwordx4 v[38:41], v[156:157], off offset:528
	global_load_dwordx4 v[46:49], v[156:157], off offset:512
	global_load_dwordx4 v[42:45], v[154:155], off offset:528
	global_load_dwordx4 v[50:53], v[154:155], off offset:512
	v_lshlrev_b32_e32 v0, 6, v96
	v_and_or_b32 v0, v0, s1, v196
	v_lshlrev_b32_e32 v0, 1, v0
	s_waitcnt vmcnt(10)
; __device__ __forceinline__ size_t blk_off(int r, int c, int K) { return (size_t)(r >> 8) * 256 * K + (size_t)(c >> 6) * (256 * 64) + (size_t)((r & 255) * 64 + (c & 63)); }
; __device__ __forceinline__ u32x4 pack8(const f32x4 a, const f32x4 b) { u32x4 w; w.x = cvt_pk_bf16(a[0], a[1]); w.y = cvt_pk_bf16(a[2], a[3]); w.z = cvt_pk_bf16(b[0], b[1]); w.w = cvt_pk_bf16(b[2], b[3]); return w; }
;     __device__ __forceinline__ void operator()(const f32x4 (&acc)[2][2][4][2], const pg8::Unit& u, int wr, int wc, int fr, int fq) const {
;     ...
;             for (int m = 0; m < 4; ++m) { const int row = row0 + ai * 128 + m * 16; const float mu = mu4[m], rs = rs4[m];
;                 f32x4 yv[2][2], gq[2][2], bq_[2][2];
; #pragma unroll
;                 for (int bj = 0; bj < 2; ++bj)
; #pragma unroll
;                     for (int n = 0; n < 2; ++n) { yv[bj][n] = *(const f32x4*)(Yin + (size_t)row * D_ + col0 + bj * 128 + 4 * n); gq[bj][n] = *(const f32x4*)(g + col0 + bj * 128 + 4 * n); bq_[bj][n] = *(const f32x4*)(b + col0 + bj * 128 + 4 * n); }
;                 asm volatile("" ::: "memory");
;                 float s1 = 0.f, s2 = 0.f;
; #pragma unroll
;                 for (int bj = 0; bj < 2; ++bj) { float* yp = Y + (size_t)row * D_ + col0 + bj * 128; f32x4 v[2];
; #pragma unroll
;                     for (int n = 0; n < 2; ++n) { v[n] = (((yv[bj][n] - mu) * rs) * gq[bj][n] + bq_[bj][n]) * ALPHA_ + acc[ai][bj][m][n] * sc;
;                         *(f32x4*)(yp + 4 * n) = v[n]; s1 += (v[n][0] + v[n][1]) + (v[n][2] + v[n][3]); s2 += (v[n][0] * v[n][0] + v[n][1] * v[n][1]) + (v[n][2] * v[n][2] + v[n][3] * v[n][3]); }
;                     *(u32x4*)(Yb + blk_off(row, col0 + bj * 128, D_)) = pack8(v[0], v[1]); }
	v_sub_f32_e32 v67, v67, v59
	v_sub_f32_e32 v66, v66, v59
	v_sub_f32_e32 v69, v69, v59
	v_sub_f32_e32 v68, v68, v59
	v_pk_mul_f32 v[68:69], v[58:59], v[68:69] op_sel_hi:[0,1]
	v_pk_mul_f32 v[66:67], v[58:59], v[66:67] op_sel_hi:[0,1]
	s_waitcnt vmcnt(6)
	v_pk_fma_f32 v[66:67], v[78:79], v[66:67], v[86:87]
	v_pk_fma_f32 v[68:69], v[80:81], v[68:69], v[88:89]
	v_pk_fma_f32 v[66:67], v[66:67], s[2:3], v[30:31] op_sel_hi:[1,0,1]
	v_pk_fma_f32 v[68:69], v[68:69], s[2:3], v[32:33] op_sel_hi:[1,0,1]
	v_add_f32_e32 v30, v66, v67
	v_add_f32_e32 v31, v68, v69
	v_add_f32_e32 v30, v30, v31
	v_add_f32_e32 v78, 0, v30
	v_mul_f32_e32 v30, v67, v67
	v_mul_f32_e32 v31, v69, v69
	v_fmac_f32_e32 v30, v66, v66
	v_fmac_f32_e32 v31, v68, v68
	v_add_f32_e32 v79, v30, v31
	v_sub_f32_e32 v31, v63, v59
	v_sub_f32_e32 v30, v62, v59
	v_sub_f32_e32 v33, v65, v59
	v_sub_f32_e32 v32, v64, v59
	v_pk_mul_f32 v[32:33], v[58:59], v[32:33] op_sel_hi:[0,1]
	v_pk_mul_f32 v[30:31], v[58:59], v[30:31] op_sel_hi:[0,1]
	v_pk_fma_f32 v[30:31], v[70:71], v[30:31], v[82:83]
	v_pk_fma_f32 v[32:33], v[72:73], v[32:33], v[84:85]
	v_pk_fma_f32 v[62:63], v[30:31], s[2:3], v[26:27] op_sel_hi:[1,0,1]
	v_pk_fma_f32 v[64:65], v[32:33], s[2:3], v[28:29] op_sel_hi:[1,0,1]
	v_add_f32_e32 v26, v62, v63
	v_add_f32_e32 v27, v64, v65
	v_add_f32_e32 v26, v26, v27
	v_add_f32_e32 v31, v78, v26
	v_mul_f32_e32 v26, v63, v63
	v_mul_f32_e32 v27, v65, v65
	v_fmac_f32_e32 v26, v62, v62
	v_fmac_f32_e32 v27, v64, v64
	v_add_f32_e32 v26, v26, v27
	v_add_f32_e32 v30, v79, v26
	v_cvt_pk_bf16_f32 v26, v66, v67
	v_cvt_pk_bf16_f32 v27, v68, v69
	v_cvt_pk_bf16_f32 v28, v62, v63
	v_cvt_pk_bf16_f32 v29, v64, v65
	v_lshl_add_u64 v[32:33], v[76:77], 0, v[0:1]
	s_nop 0
	s_nop 1
	v_bfe_u32 v71, v227, 4, 2
	v_sub_u32_e32 v70, 0, v71
	v_lshlrev_b32_e32 v70, 4, v70
	v_ashrrev_i32_e32 v71, 31, v70
	v_lshl_add_u64 v[70:71], v[60:61], 0, v[70:71]
	v_permlane16_swap_b32_e32 v66, v62
	v_permlane16_swap_b32_e32 v67, v63
	v_permlane16_swap_b32_e32 v68, v64
	v_permlane16_swap_b32_e32 v69, v65
	v_permlane32_swap_b32_e32 v66, v62
	v_permlane32_swap_b32_e32 v67, v63
	v_permlane32_swap_b32_e32 v68, v64
	v_permlane32_swap_b32_e32 v69, v65
	v_mov_b32_e32 v78, v66
	v_mov_b32_e32 v79, v67
	v_mov_b32_e32 v80, v68
	v_mov_b32_e32 v81, v69
	v_bfe_u32 v72, v227, 3, 1
	v_mul_i32_i24_e32 v72, 0xffff8040, v72
	v_ashrrev_i32_e32 v73, 31, v72
	v_lshl_add_u64 v[70:71], v[70:71], 0, v[72:73]
	v_mov_b32_e32 v72, 0x8000
	v_mov_b32_e32 v73, 0
	v_lshl_add_u64 v[72:73], v[70:71], 0, v[72:73]
	v_mov_b32_dpp v66, v62 row_ror:8 row_mask:0xf bank_mask:0xc
	v_mov_b32_dpp v67, v63 row_ror:8 row_mask:0xf bank_mask:0xc
	v_mov_b32_dpp v68, v64 row_ror:8 row_mask:0xf bank_mask:0xc
	v_mov_b32_dpp v69, v65 row_ror:8 row_mask:0xf bank_mask:0xc
	v_mov_b32_dpp v62, v78 row_ror:8 row_mask:0xf bank_mask:0x3
	v_mov_b32_dpp v63, v79 row_ror:8 row_mask:0xf bank_mask:0x3
	v_mov_b32_dpp v64, v80 row_ror:8 row_mask:0xf bank_mask:0x3
	v_mov_b32_dpp v65, v81 row_ror:8 row_mask:0xf bank_mask:0x3
	global_store_dwordx4 v[70:71], v[66:69], off
	global_store_dwordx4 v[72:73], v[62:65], off
	s_nop 1
	global_store_dwordx4 v[32:33], v[26:29], off
	s_waitcnt vmcnt(7)
	s_nop 0
	v_sub_f32_e32 v27, v55, v59
	v_sub_f32_e32 v26, v54, v59
	v_sub_f32_e32 v29, v57, v59
	v_sub_f32_e32 v28, v56, v59
	v_pk_mul_f32 v[28:29], v[58:59], v[28:29] op_sel_hi:[0,1]
	v_pk_mul_f32 v[26:27], v[58:59], v[26:27] op_sel_hi:[0,1]
	s_waitcnt vmcnt(3)
	v_pk_fma_f32 v[26:27], v[46:47], v[26:27], v[50:51]
	v_pk_fma_f32 v[28:29], v[48:49], v[28:29], v[52:53]
	v_pk_fma_f32 v[22:23], v[26:27], s[2:3], v[22:23] op_sel_hi:[1,0,1]
	v_pk_fma_f32 v[24:25], v[28:29], s[2:3], v[24:25] op_sel_hi:[1,0,1]
	v_add_f32_e32 v26, v22, v23
	v_add_f32_e32 v27, v24, v25
	v_add_f32_e32 v26, v26, v27
	v_add_f32_e32 v31, v31, v26
	v_mul_f32_e32 v26, v23, v23
	v_mul_f32_e32 v27, v25, v25
	v_fmac_f32_e32 v26, v22, v22
	v_fmac_f32_e32 v27, v24, v24
	v_add_f32_e32 v26, v26, v27
	v_add_f32_e32 v30, v30, v26
	v_sub_f32_e32 v27, v35, v59
	v_sub_f32_e32 v26, v34, v59
	v_sub_f32_e32 v29, v37, v59
	v_sub_f32_e32 v28, v36, v59
	v_pk_mul_f32 v[28:29], v[58:59], v[28:29] op_sel_hi:[0,1]
	v_pk_mul_f32 v[26:27], v[58:59], v[26:27] op_sel_hi:[0,1]
	v_pk_fma_f32 v[26:27], v[38:39], v[26:27], v[42:43]
	v_pk_fma_f32 v[28:29], v[40:41], v[28:29], v[44:45]
	v_pk_fma_f32 v[18:19], v[26:27], s[2:3], v[18:19] op_sel_hi:[1,0,1]
	v_pk_fma_f32 v[20:21], v[28:29], s[2:3], v[20:21] op_sel_hi:[1,0,1]
	v_add_f32_e32 v26, v18, v19
	v_add_f32_e32 v27, v20, v21
	v_add_f32_e32 v26, v26, v27
	v_mul_f32_e32 v27, v19, v19
	v_mul_f32_e32 v28, v21, v21
	v_add_f32_e32 v26, v31, v26
	v_fmac_f32_e32 v27, v18, v18
	v_fmac_f32_e32 v28, v20, v20
	s_nop 0
	s_nop 1
	v_bfe_u32 v33, v227, 4, 2
	v_sub_u32_e32 v32, 0, v33
	v_lshlrev_b32_e32 v32, 4, v32
	v_ashrrev_i32_e32 v33, 31, v32
	v_lshl_add_u64 v[32:33], v[60:61], 0, v[32:33]
	v_permlane16_swap_b32_e32 v22, v18
	v_permlane16_swap_b32_e32 v23, v19
	v_permlane16_swap_b32_e32 v24, v20
	v_permlane16_swap_b32_e32 v25, v21
	v_permlane32_swap_b32_e32 v22, v18
	v_permlane32_swap_b32_e32 v23, v19
	v_permlane32_swap_b32_e32 v24, v20
	v_permlane32_swap_b32_e32 v25, v21
	v_mov_b32_e32 v29, v22
	v_mov_b32_e32 v36, v23
	v_mov_b32_e32 v37, v24
	v_mov_b32_e32 v38, v25
	v_bfe_u32 v34, v227, 3, 1
	v_mul_i32_i24_e32 v34, 0xffff8040, v34
	v_ashrrev_i32_e32 v35, 31, v34
	v_lshl_add_u64 v[32:33], v[32:33], 0, v[34:35]
	v_mov_b32_e32 v34, 0x8000
	v_mov_b32_e32 v35, 0
	v_lshl_add_u64 v[34:35], v[32:33], 0, v[34:35]
	v_mov_b32_dpp v22, v18 row_ror:8 row_mask:0xf bank_mask:0xc
	v_mov_b32_dpp v23, v19 row_ror:8 row_mask:0xf bank_mask:0xc
; __device__ __forceinline__ float xsum16(float v) { const auto r = __builtin_amdgcn_permlane16_swap(__float_as_uint(v), __float_as_uint(v), false, false); return __uint_as_float(r[0]) + __uint_as_float(r[1]); }
; __device__ __forceinline__ float xsum32(float v) { const auto r = __builtin_amdgcn_permlane32_swap(__float_as_uint(v), __float_as_uint(v), false, false); return __uint_as_float(r[0]) + __uint_as_float(r[1]); }
; __device__ __forceinline__ size_t blk_off(int r, int c, int K) { return (size_t)(r >> 8) * 256 * K + (size_t)(c >> 6) * (256 * 64) + (size_t)((r & 255) * 64 + (c & 63)); }
; __device__ __forceinline__ u32x4 pack8(const f32x4 a, const f32x4 b) { u32x4 w; w.x = cvt_pk_bf16(a[0], a[1]); w.y = cvt_pk_bf16(a[2], a[3]); w.z = cvt_pk_bf16(b[0], b[1]); w.w = cvt_pk_bf16(b[2], b[3]); return w; }
;     __device__ __forceinline__ void operator()(const f32x4 (&acc)[2][2][4][2], const pg8::Unit& u, int wr, int wc, int fr, int fq) const {
;     ...
;             for (int m = 0; m < 4; ++m) { const int row = row0 + ai * 128 + m * 16; const float mu = mu4[m], rs = rs4[m];
;                 f32x4 yv[2][2], gq[2][2], bq_[2][2];
; #pragma unroll
;                 for (int bj = 0; bj < 2; ++bj)
; #pragma unroll
;                     for (int n = 0; n < 2; ++n) { yv[bj][n] = *(const f32x4*)(Yin + (size_t)row * D_ + col0 + bj * 128 + 4 * n); gq[bj][n] = *(const f32x4*)(g + col0 + bj * 128 + 4 * n); bq_[bj][n] = *(const f32x4*)(b + col0 + bj * 128 + 4 * n); }
;                 asm volatile("" ::: "memory");
;                 float s1 = 0.f, s2 = 0.f;
; #pragma unroll
;                 for (int bj = 0; bj < 2; ++bj) { float* yp = Y + (size_t)row * D_ + col0 + bj * 128; f32x4 v[2];
; #pragma unroll
;                     for (int n = 0; n < 2; ++n) { v[n] = (((yv[bj][n] - mu) * rs) * gq[bj][n] + bq_[bj][n]) * ALPHA_ + acc[ai][bj][m][n] * sc;
;                         *(f32x4*)(yp + 4 * n) = v[n]; s1 += (v[n][0] + v[n][1]) + (v[n][2] + v[n][3]); s2 += (v[n][0] * v[n][0] + v[n][1] * v[n][1]) + (v[n][2] * v[n][2] + v[n][3] * v[n][3]); }
;                     *(u32x4*)(Yb + blk_off(row, col0 + bj * 128, D_)) = pack8(v[0], v[1]); }
;                 s1 = xsum32(xsum16(s1)); s2 = xsum32(xsum16(s2));
;                 if (fq == 0) *(f32x2*)(stn + (size_t)row * 32 + (u.pn * 4 + wc) * 2) = (f32x2){s1, s2}; asm volatile("" ::: "memory"); } }
	v_mov_b32_dpp v24, v20 row_ror:8 row_mask:0xf bank_mask:0xc
	v_mov_b32_dpp v25, v21 row_ror:8 row_mask:0xf bank_mask:0xc
	v_mov_b32_dpp v18, v29 row_ror:8 row_mask:0xf bank_mask:0x3
	v_mov_b32_dpp v19, v36 row_ror:8 row_mask:0xf bank_mask:0x3
	v_mov_b32_dpp v20, v37 row_ror:8 row_mask:0xf bank_mask:0x3
	v_mov_b32_dpp v21, v38 row_ror:8 row_mask:0xf bank_mask:0x3
	global_store_dwordx4 v[32:33], v[22:25], off offset:512
	global_store_dwordx4 v[34:35], v[18:21], off offset:512
	s_nop 1
	v_mov_b32_dpp v18, v22 row_ror:8 row_mask:0xf bank_mask:0x3
	v_mov_b32_dpp v19, v23 row_ror:8 row_mask:0xf bank_mask:0x3
	v_mov_b32_dpp v20, v24 row_ror:8 row_mask:0xf bank_mask:0x3
	v_mov_b32_dpp v21, v25 row_ror:8 row_mask:0xf bank_mask:0x3
	v_mov_b32_e32 v22, v29
	v_mov_b32_e32 v23, v36
	v_mov_b32_e32 v24, v37
	v_mov_b32_e32 v25, v38
	s_nop 1
	v_permlane32_swap_b32_e32 v22, v18
	v_permlane32_swap_b32_e32 v23, v19
	v_permlane32_swap_b32_e32 v24, v20
	v_permlane32_swap_b32_e32 v25, v21
	v_permlane16_swap_b32_e32 v22, v18
	v_permlane16_swap_b32_e32 v23, v19
	v_permlane16_swap_b32_e32 v24, v20
	v_permlane16_swap_b32_e32 v25, v21
	v_add_f32_e32 v27, v27, v28
	v_cvt_pk_bf16_f32 v22, v22, v23
	v_cvt_pk_bf16_f32 v23, v24, v25
	v_cvt_pk_bf16_f32 v24, v18, v19
	v_lshl_add_u64 v[18:19], v[74:75], 0, v[0:1]
	v_mov_b32_e32 v0, v26
	v_add_f32_e32 v27, v30, v27
	v_cvt_pk_bf16_f32 v25, v20, v21
	v_permlane16_swap_b32_e32 v26, v0
	global_store_dwordx4 v[18:19], v[22:25], off
	v_add_f32_e32 v18, v26, v0
	v_mov_b32_e32 v0, v27
	s_nop 1
	v_permlane16_swap_b32_e32 v27, v0
	v_add_f32_e32 v19, v27, v0
	v_mov_b32_e32 v20, v18
	v_mov_b32_e32 v21, v19
	s_nop 0
	v_permlane32_swap_b32_e32 v18, v20
	v_permlane32_swap_b32_e32 v19, v21
	s_and_saveexec_b64 s[24:25], s[44:45]
	s_cbranch_execz .LBB0_1549
	v_pk_add_f32 v[18:19], v[18:19], v[20:21]
	v_lshlrev_b64 v[20:21], 7, v[96:97]
	v_lshl_add_u64 v[20:21], s[6:7], 0, v[20:21]
	v_lshl_add_u64 v[20:21], s[52:53], 2, v[20:21]
	global_store_dwordx2 v[20:21], v[18:19], off
.LBB0_1549:
	s_or_b64 exec, exec, s[24:25]
	v_pk_add_f32 v[18:19], v[98:99], v[100:101]
	s_mov_b32 s2, 0x3a800000
	v_pk_mul_f32 v[42:43], v[18:19], s[2:3] op_sel_hi:[1,0]
	s_mov_b32 s1, 0x800000
	v_fma_f32 v0, -v43, v43, v42
	v_max_f32_e32 v0, 0, v0
	v_add_f32_e32 v0, 0x3727c5ac, v0
	v_cmp_gt_f32_e32 vcc, s1, v0
	v_mul_f32_e32 v18, 0x4b800000, v0
	s_load_dwordx16 s[64:79], s[34:35], 0x38
	v_cndmask_b32_e32 v0, v0, v18, vcc
	v_rsq_f32_e32 v0, v0
	s_mov_b32 s2, 0x3fd744fd
	s_movk_i32 s1, 0x3fc0
	v_mul_f32_e32 v18, 0x45800000, v0
	v_cndmask_b32_e32 v42, v0, v18, vcc
	v_lshlrev_b64 v[18:19], 12, v[94:95]
	s_waitcnt lgkmcnt(0)
	v_lshl_add_u64 v[18:19], s[78:79], 0, v[18:19]
	v_lshl_add_u64 v[44:45], v[152:153], 2, v[18:19]
	global_load_dwordx4 v[46:49], v[44:45], off offset:16
	global_load_dwordx4 v[50:53], v[44:45], off
	global_load_dwordx4 v[54:57], v[156:157], off offset:16
	global_load_dwordx4 v[58:61], v[156:157], off
	global_load_dwordx4 v[62:65], v[154:155], off offset:16
	global_load_dwordx4 v[66:69], v[154:155], off
	global_load_dwordx4 v[18:21], v[44:45], off offset:528
	global_load_dwordx4 v[38:41], v[44:45], off offset:512
	global_load_dwordx4 v[22:25], v[156:157], off offset:528
	global_load_dwordx4 v[30:33], v[156:157], off offset:512
	global_load_dwordx4 v[26:29], v[154:155], off offset:528
	global_load_dwordx4 v[34:37], v[154:155], off offset:512
	v_lshlrev_b32_e32 v0, 6, v94
	v_and_or_b32 v0, v0, s1, v196
	v_lshlrev_b32_e32 v0, 1, v0
	s_waitcnt vmcnt(10)
	v_sub_f32_e32 v51, v51, v43
	v_sub_f32_e32 v50, v50, v43
	v_sub_f32_e32 v53, v53, v43
	v_sub_f32_e32 v52, v52, v43
	v_pk_mul_f32 v[52:53], v[42:43], v[52:53] op_sel_hi:[0,1]
	v_pk_mul_f32 v[50:51], v[42:43], v[50:51] op_sel_hi:[0,1]
	s_waitcnt vmcnt(6)
	v_pk_fma_f32 v[50:51], v[58:59], v[50:51], v[66:67]
	v_pk_fma_f32 v[52:53], v[60:61], v[52:53], v[68:69]
	v_pk_fma_f32 v[50:51], v[50:51], s[2:3], v[14:15] op_sel_hi:[1,0,1]
	v_pk_fma_f32 v[52:53], v[52:53], s[2:3], v[16:17] op_sel_hi:[1,0,1]
	v_add_f32_e32 v14, v50, v51
	v_add_f32_e32 v15, v52, v53
	v_add_f32_e32 v14, v14, v15
	v_add_f32_e32 v58, 0, v14
	v_mul_f32_e32 v14, v51, v51
	v_mul_f32_e32 v15, v53, v53
	v_fmac_f32_e32 v14, v50, v50
	v_fmac_f32_e32 v15, v52, v52
	v_add_f32_e32 v59, v14, v15
	v_sub_f32_e32 v15, v47, v43
	v_sub_f32_e32 v14, v46, v43
	v_sub_f32_e32 v17, v49, v43
	v_sub_f32_e32 v16, v48, v43
	v_pk_mul_f32 v[16:17], v[42:43], v[16:17] op_sel_hi:[0,1]
	v_pk_mul_f32 v[14:15], v[42:43], v[14:15] op_sel_hi:[0,1]
	v_pk_fma_f32 v[14:15], v[54:55], v[14:15], v[62:63]
	v_pk_fma_f32 v[16:17], v[56:57], v[16:17], v[64:65]
	v_pk_fma_f32 v[46:47], v[14:15], s[2:3], v[10:11] op_sel_hi:[1,0,1]
	v_pk_fma_f32 v[48:49], v[16:17], s[2:3], v[12:13] op_sel_hi:[1,0,1]
	v_add_f32_e32 v10, v46, v47
	v_add_f32_e32 v11, v48, v49
	v_add_f32_e32 v10, v10, v11
	v_add_f32_e32 v15, v58, v10
	v_mul_f32_e32 v10, v47, v47
	v_mul_f32_e32 v11, v49, v49
	v_fmac_f32_e32 v10, v46, v46
	v_fmac_f32_e32 v11, v48, v48
	v_add_f32_e32 v10, v10, v11
	v_add_f32_e32 v14, v59, v10
	v_cvt_pk_bf16_f32 v10, v50, v51
	v_cvt_pk_bf16_f32 v11, v52, v53
	v_cvt_pk_bf16_f32 v12, v46, v47
	v_cvt_pk_bf16_f32 v13, v48, v49
	v_lshl_add_u64 v[16:17], v[76:77], 0, v[0:1]
	s_nop 0
	s_nop 1
	v_bfe_u32 v55, v227, 4, 2
	v_sub_u32_e32 v54, 0, v55
	v_lshlrev_b32_e32 v54, 4, v54
	v_ashrrev_i32_e32 v55, 31, v54
	v_lshl_add_u64 v[54:55], v[44:45], 0, v[54:55]
	v_permlane16_swap_b32_e32 v50, v46
	v_permlane16_swap_b32_e32 v51, v47
	v_permlane16_swap_b32_e32 v52, v48
	v_permlane16_swap_b32_e32 v53, v49
	v_permlane32_swap_b32_e32 v50, v46
	v_permlane32_swap_b32_e32 v51, v47
	v_permlane32_swap_b32_e32 v52, v48
	v_permlane32_swap_b32_e32 v53, v49
	v_mov_b32_e32 v58, v50
	v_mov_b32_e32 v59, v51
	v_mov_b32_e32 v60, v52
	v_mov_b32_e32 v61, v53
	v_bfe_u32 v56, v227, 3, 1
	v_mul_i32_i24_e32 v56, 0xffff8040, v56
	v_ashrrev_i32_e32 v57, 31, v56
	v_lshl_add_u64 v[54:55], v[54:55], 0, v[56:57]
	v_mov_b32_e32 v56, 0x8000
	v_mov_b32_e32 v57, 0
	v_lshl_add_u64 v[56:57], v[54:55], 0, v[56:57]
	v_mov_b32_dpp v50, v46 row_ror:8 row_mask:0xf bank_mask:0xc
	v_mov_b32_dpp v51, v47 row_ror:8 row_mask:0xf bank_mask:0xc
	v_mov_b32_dpp v52, v48 row_ror:8 row_mask:0xf bank_mask:0xc
	v_mov_b32_dpp v53, v49 row_ror:8 row_mask:0xf bank_mask:0xc
	v_mov_b32_dpp v46, v58 row_ror:8 row_mask:0xf bank_mask:0x3
	v_mov_b32_dpp v47, v59 row_ror:8 row_mask:0xf bank_mask:0x3
	v_mov_b32_dpp v48, v60 row_ror:8 row_mask:0xf bank_mask:0x3
	v_mov_b32_dpp v49, v61 row_ror:8 row_mask:0xf bank_mask:0x3
	global_store_dwordx4 v[54:55], v[50:53], off
	global_store_dwordx4 v[56:57], v[46:49], off
	s_nop 1
	global_store_dwordx4 v[16:17], v[10:13], off
	s_waitcnt vmcnt(7)
; __device__ __forceinline__ float xsum16(float v) { const auto r = __builtin_amdgcn_permlane16_swap(__float_as_uint(v), __float_as_uint(v), false, false); return __uint_as_float(r[0]) + __uint_as_float(r[1]); }
; __device__ __forceinline__ float xsum32(float v) { const auto r = __builtin_amdgcn_permlane32_swap(__float_as_uint(v), __float_as_uint(v), false, false); return __uint_as_float(r[0]) + __uint_as_float(r[1]); }
; __device__ __forceinline__ size_t blk_off(int r, int c, int K) { return (size_t)(r >> 8) * 256 * K + (size_t)(c >> 6) * (256 * 64) + (size_t)((r & 255) * 64 + (c & 63)); }
; __device__ __forceinline__ u32x4 pack8(const f32x4 a, const f32x4 b) { u32x4 w; w.x = cvt_pk_bf16(a[0], a[1]); w.y = cvt_pk_bf16(a[2], a[3]); w.z = cvt_pk_bf16(b[0], b[1]); w.w = cvt_pk_bf16(b[2], b[3]); return w; }
;     __device__ __forceinline__ void operator()(const f32x4 (&acc)[2][2][4][2], const pg8::Unit& u, int wr, int wc, int fr, int fq) const {
;     ...
;                 for (int bj = 0; bj < 2; ++bj) { float* yp = Y + (size_t)row * D_ + col0 + bj * 128; f32x4 v[2];
; #pragma unroll
;                     for (int n = 0; n < 2; ++n) { v[n] = (((yv[bj][n] - mu) * rs) * gq[bj][n] + bq_[bj][n]) * ALPHA_ + acc[ai][bj][m][n] * sc;
;                         *(f32x4*)(yp + 4 * n) = v[n]; s1 += (v[n][0] + v[n][1]) + (v[n][2] + v[n][3]); s2 += (v[n][0] * v[n][0] + v[n][1] * v[n][1]) + (v[n][2] * v[n][2] + v[n][3] * v[n][3]); }
;                     *(u32x4*)(Yb + blk_off(row, col0 + bj * 128, D_)) = pack8(v[0], v[1]); }
;                 s1 = xsum32(xsum16(s1)); s2 = xsum32(xsum16(s2));
;                 if (fq == 0) *(f32x2*)(stn + (size_t)row * 32 + (u.pn * 4 + wc) * 2) = (f32x2){s1, s2}; asm volatile("" ::: "memory"); } }
	s_nop 0
	v_sub_f32_e32 v11, v39, v43
	v_sub_f32_e32 v10, v38, v43
	v_sub_f32_e32 v13, v41, v43
	v_sub_f32_e32 v12, v40, v43
	v_pk_mul_f32 v[12:13], v[42:43], v[12:13] op_sel_hi:[0,1]
	v_pk_mul_f32 v[10:11], v[42:43], v[10:11] op_sel_hi:[0,1]
	s_waitcnt vmcnt(3)
	v_pk_fma_f32 v[10:11], v[30:31], v[10:11], v[34:35]
	v_pk_fma_f32 v[12:13], v[32:33], v[12:13], v[36:37]
	v_pk_fma_f32 v[6:7], v[10:11], s[2:3], v[6:7] op_sel_hi:[1,0,1]
	v_pk_fma_f32 v[8:9], v[12:13], s[2:3], v[8:9] op_sel_hi:[1,0,1]
	v_add_f32_e32 v10, v6, v7
	v_add_f32_e32 v11, v8, v9
	v_add_f32_e32 v10, v10, v11
	v_add_f32_e32 v15, v15, v10
	v_mul_f32_e32 v10, v7, v7
	v_mul_f32_e32 v11, v9, v9
	v_fmac_f32_e32 v10, v6, v6
	v_fmac_f32_e32 v11, v8, v8
	v_add_f32_e32 v10, v10, v11
	v_add_f32_e32 v14, v14, v10
	v_sub_f32_e32 v11, v19, v43
	v_sub_f32_e32 v10, v18, v43
	v_sub_f32_e32 v13, v21, v43
	v_sub_f32_e32 v12, v20, v43
	v_pk_mul_f32 v[12:13], v[42:43], v[12:13] op_sel_hi:[0,1]
	v_pk_mul_f32 v[10:11], v[42:43], v[10:11] op_sel_hi:[0,1]
	v_pk_fma_f32 v[10:11], v[22:23], v[10:11], v[26:27]
	v_pk_fma_f32 v[12:13], v[24:25], v[12:13], v[28:29]
	v_pk_fma_f32 v[2:3], v[10:11], s[2:3], v[2:3] op_sel_hi:[1,0,1]
	v_pk_fma_f32 v[4:5], v[12:13], s[2:3], v[4:5] op_sel_hi:[1,0,1]
	v_add_f32_e32 v10, v2, v3
	v_add_f32_e32 v11, v4, v5
	v_add_f32_e32 v10, v10, v11
	v_mul_f32_e32 v11, v3, v3
	v_mul_f32_e32 v12, v5, v5
	v_add_f32_e32 v10, v15, v10
	v_fmac_f32_e32 v11, v2, v2
	v_fmac_f32_e32 v12, v4, v4
	s_nop 0
	s_nop 1
	v_bfe_u32 v17, v227, 4, 2
	v_sub_u32_e32 v16, 0, v17
	v_lshlrev_b32_e32 v16, 4, v16
	v_ashrrev_i32_e32 v17, 31, v16
	v_lshl_add_u64 v[16:17], v[44:45], 0, v[16:17]
	v_permlane16_swap_b32_e32 v6, v2
	v_permlane16_swap_b32_e32 v7, v3
	v_permlane16_swap_b32_e32 v8, v4
	v_permlane16_swap_b32_e32 v9, v5
	v_permlane32_swap_b32_e32 v6, v2
	v_permlane32_swap_b32_e32 v7, v3
	v_permlane32_swap_b32_e32 v8, v4
	v_permlane32_swap_b32_e32 v9, v5
	v_mov_b32_e32 v13, v6
	v_mov_b32_e32 v20, v7
	v_mov_b32_e32 v21, v8
	v_mov_b32_e32 v22, v9
	v_bfe_u32 v18, v227, 3, 1
	v_mul_i32_i24_e32 v18, 0xffff8040, v18
	v_ashrrev_i32_e32 v19, 31, v18
	v_lshl_add_u64 v[16:17], v[16:17], 0, v[18:19]
	v_mov_b32_e32 v18, 0x8000
	v_mov_b32_e32 v19, 0
	v_lshl_add_u64 v[18:19], v[16:17], 0, v[18:19]
	v_mov_b32_dpp v6, v2 row_ror:8 row_mask:0xf bank_mask:0xc
	v_mov_b32_dpp v7, v3 row_ror:8 row_mask:0xf bank_mask:0xc
	v_mov_b32_dpp v8, v4 row_ror:8 row_mask:0xf bank_mask:0xc
	v_mov_b32_dpp v9, v5 row_ror:8 row_mask:0xf bank_mask:0xc
	v_mov_b32_dpp v2, v13 row_ror:8 row_mask:0xf bank_mask:0x3
	v_mov_b32_dpp v3, v20 row_ror:8 row_mask:0xf bank_mask:0x3
	v_mov_b32_dpp v4, v21 row_ror:8 row_mask:0xf bank_mask:0x3
	v_mov_b32_dpp v5, v22 row_ror:8 row_mask:0xf bank_mask:0x3
	global_store_dwordx4 v[16:17], v[6:9], off offset:512
	global_store_dwordx4 v[18:19], v[2:5], off offset:512
	s_nop 1
	v_mov_b32_dpp v2, v6 row_ror:8 row_mask:0xf bank_mask:0x3
	v_mov_b32_dpp v3, v7 row_ror:8 row_mask:0xf bank_mask:0x3
	v_mov_b32_dpp v4, v8 row_ror:8 row_mask:0xf bank_mask:0x3
	v_mov_b32_dpp v5, v9 row_ror:8 row_mask:0xf bank_mask:0x3
	v_mov_b32_e32 v6, v13
	v_mov_b32_e32 v7, v20
	v_mov_b32_e32 v8, v21
	v_mov_b32_e32 v9, v22
	s_nop 1
	v_permlane32_swap_b32_e32 v6, v2
	v_permlane32_swap_b32_e32 v7, v3
	v_permlane32_swap_b32_e32 v8, v4
	v_permlane32_swap_b32_e32 v9, v5
	v_permlane16_swap_b32_e32 v6, v2
	v_permlane16_swap_b32_e32 v7, v3
	v_permlane16_swap_b32_e32 v8, v4
	v_permlane16_swap_b32_e32 v9, v5
	v_add_f32_e32 v11, v11, v12
	v_cvt_pk_bf16_f32 v6, v6, v7
	v_cvt_pk_bf16_f32 v7, v8, v9
	v_cvt_pk_bf16_f32 v8, v2, v3
	v_lshl_add_u64 v[2:3], v[74:75], 0, v[0:1]
	v_mov_b32_e32 v0, v10
	v_add_f32_e32 v11, v14, v11
	v_cvt_pk_bf16_f32 v9, v4, v5
	v_permlane16_swap_b32_e32 v10, v0
	global_store_dwordx4 v[2:3], v[6:9], off
	v_add_f32_e32 v2, v10, v0
	v_mov_b32_e32 v0, v11
	s_nop 1
	v_permlane16_swap_b32_e32 v11, v0
	v_add_f32_e32 v3, v11, v0
	v_mov_b32_e32 v4, v2
	v_mov_b32_e32 v5, v3
	s_nop 0
	v_permlane32_swap_b32_e32 v2, v4
	v_permlane32_swap_b32_e32 v3, v5
	s_and_saveexec_b64 s[24:25], s[44:45]
	s_cbranch_execz .LBB0_1551
	v_pk_add_f32 v[2:3], v[2:3], v[4:5]
	v_lshlrev_b64 v[4:5], 7, v[94:95]
	v_lshl_add_u64 v[4:5], s[6:7], 0, v[4:5]
	v_lshl_add_u64 v[4:5], s[52:53], 2, v[4:5]
	global_store_dwordx2 v[4:5], v[2:3], off

; __device__ __forceinline__ size_t blk_off(int r, int c, int K) { return (size_t)(r >> 8) * 256 * K + (size_t)(c >> 6) * (256 * 64) + (size_t)((r & 255) * 64 + (c & 63)); }
; __device__ __forceinline__ u32x4 pack8(const f32x4 a, const f32x4 b) { u32x4 w; w.x = cvt_pk_bf16(a[0], a[1]); w.y = cvt_pk_bf16(a[2], a[3]); w.z = cvt_pk_bf16(b[0], b[1]); w.w = cvt_pk_bf16(b[2], b[3]); return w; }
;     __device__ __forceinline__ void operator()(const f32x4 (&acc)[2][2][4][2], const pg8::Unit& u, int wr, int wc, int fr, int fq) const {
;     ...
;             for (int m = 0; m < 4; ++m) { const int row = row0 + ai * 128 + m * 16; const float mu = mu4[m], rs = rs4[m];
;                 f32x4 yv[2][2], gq[2][2], bq_[2][2];
; #pragma unroll
;                 for (int bj = 0; bj < 2; ++bj)
; #pragma unroll
;                     for (int n = 0; n < 2; ++n) { yv[bj][n] = *(const f32x4*)(Yin + (size_t)row * D_ + col0 + bj * 128 + 4 * n); gq[bj][n] = *(const f32x4*)(g + col0 + bj * 128 + 4 * n); bq_[bj][n] = *(const f32x4*)(b + col0 + bj * 128 + 4 * n); }
;                 asm volatile("" ::: "memory");
;                 float s1 = 0.f, s2 = 0.f;
; #pragma unroll
;                 for (int bj = 0; bj < 2; ++bj) { float* yp = Y + (size_t)row * D_ + col0 + bj * 128; f32x4 v[2];
; #pragma unroll
;                     for (int n = 0; n < 2; ++n) { v[n] = (((yv[bj][n] - mu) * rs) * gq[bj][n] + bq_[bj][n]) * ALPHA_ + acc[ai][bj][m][n] * sc;
;                         *(f32x4*)(yp + 4 * n) = v[n]; s1 += (v[n][0] + v[n][1]) + (v[n][2] + v[n][3]); s2 += (v[n][0] * v[n][0] + v[n][1] * v[n][1]) + (v[n][2] * v[n][2] + v[n][3] * v[n][3]); }
;                     *(u32x4*)(Yb + blk_off(row, col0 + bj * 128, D_)) = pack8(v[0], v[1]); }
.LBB0_1713:
	s_or_b64 exec, exec, s[24:25]
	v_pk_add_f32 v[50:51], v[70:71], v[72:73]
	s_mov_b32 s2, 0x3a800000
	v_pk_mul_f32 v[92:93], v[50:51], s[2:3] op_sel_hi:[1,0]
	s_mov_b32 s1, 0x800000
	v_fma_f32 v0, -v93, v93, v92
	v_max_f32_e32 v0, 0, v0
	v_add_f32_e32 v0, 0x3727c5ac, v0
	v_cmp_gt_f32_e32 vcc, s1, v0
	v_mul_f32_e32 v50, 0x4b800000, v0
	s_load_dwordx16 s[60:75], s[34:35], 0x38
	v_cndmask_b32_e32 v0, v0, v50, vcc
	v_rsq_f32_e32 v0, v0
	s_mov_b32 s2, 0x3fd744fd
	s_movk_i32 s1, 0x37c0
	v_mul_f32_e32 v50, 0x45800000, v0
	v_cndmask_b32_e32 v92, v0, v50, vcc
	v_lshlrev_b64 v[50:51], 12, v[96:97]
	s_waitcnt lgkmcnt(0)
	v_lshl_add_u64 v[50:51], s[74:75], 0, v[50:51]
	v_lshl_add_u64 v[94:95], v[152:153], 2, v[50:51]
	global_load_dwordx4 v[98:101], v[94:95], off offset:16
	global_load_dwordx4 v[102:105], v[94:95], off
	global_load_dwordx4 v[106:109], v[156:157], off offset:16
	global_load_dwordx4 v[110:113], v[156:157], off
	global_load_dwordx4 v[114:117], v[154:155], off offset:16
	global_load_dwordx4 v[118:121], v[154:155], off
	global_load_dwordx4 v[50:53], v[94:95], off offset:528
	global_load_dwordx4 v[70:73], v[94:95], off offset:512
	global_load_dwordx4 v[54:57], v[156:157], off offset:528
	global_load_dwordx4 v[62:65], v[156:157], off offset:512
	global_load_dwordx4 v[58:61], v[154:155], off offset:528
	global_load_dwordx4 v[66:69], v[154:155], off offset:512
	v_lshlrev_b32_e32 v0, 6, v96
	v_and_or_b32 v0, v0, s1, v196
	v_lshlrev_b32_e32 v0, 1, v0
	s_waitcnt vmcnt(10)
	v_sub_f32_e32 v97, v105, v93
	v_sub_f32_e32 v96, v104, v93
	v_sub_f32_e32 v103, v103, v93
	v_sub_f32_e32 v102, v102, v93
	v_pk_mul_f32 v[102:103], v[92:93], v[102:103] op_sel_hi:[0,1]
	v_pk_mul_f32 v[96:97], v[92:93], v[96:97] op_sel_hi:[0,1]
	s_waitcnt vmcnt(6)
	v_pk_fma_f32 v[96:97], v[112:113], v[96:97], v[120:121]
	v_pk_fma_f32 v[102:103], v[110:111], v[102:103], v[118:119]
	v_pk_mul_f32 v[96:97], v[96:97], s[2:3] op_sel_hi:[1,0]
	v_pk_mul_f32 v[102:103], v[102:103], s[2:3] op_sel_hi:[1,0]
	v_pk_fma_f32 v[104:105], v[48:49], 0.5, v[96:97] op_sel_hi:[1,0,1]
	v_pk_fma_f32 v[102:103], v[46:47], 0.5, v[102:103] op_sel_hi:[1,0,1]
	v_add_f32_e32 v47, v104, v105
	v_add_f32_e32 v46, v102, v103
	v_add_f32_e32 v46, v46, v47
	v_add_f32_e32 v110, 0, v46
	v_mul_f32_e32 v46, v103, v103
	v_mul_f32_e32 v47, v105, v105
	v_fmac_f32_e32 v46, v102, v102
	v_fmac_f32_e32 v47, v104, v104
	v_add_f32_e32 v111, v46, v47
	v_sub_f32_e32 v47, v101, v93
	v_sub_f32_e32 v46, v100, v93
	v_sub_f32_e32 v49, v99, v93
	v_sub_f32_e32 v48, v98, v93
	v_pk_mul_f32 v[48:49], v[92:93], v[48:49] op_sel_hi:[0,1]
	v_pk_mul_f32 v[46:47], v[92:93], v[46:47] op_sel_hi:[0,1]
	v_pk_fma_f32 v[46:47], v[108:109], v[46:47], v[116:117]
	v_pk_fma_f32 v[48:49], v[106:107], v[48:49], v[114:115]
	v_pk_mul_f32 v[46:47], v[46:47], s[2:3] op_sel_hi:[1,0]
	v_pk_mul_f32 v[48:49], v[48:49], s[2:3] op_sel_hi:[1,0]
	v_pk_fma_f32 v[98:99], v[44:45], 0.5, v[46:47] op_sel_hi:[1,0,1]
	v_pk_fma_f32 v[96:97], v[42:43], 0.5, v[48:49] op_sel_hi:[1,0,1]
	v_add_f32_e32 v43, v98, v99
	v_add_f32_e32 v42, v96, v97
	v_add_f32_e32 v42, v42, v43
	v_add_f32_e32 v47, v110, v42
	v_mul_f32_e32 v42, v97, v97
	v_mul_f32_e32 v43, v99, v99
	v_fmac_f32_e32 v42, v96, v96
	v_fmac_f32_e32 v43, v98, v98
	v_add_f32_e32 v42, v42, v43
	v_add_f32_e32 v46, v111, v42
	v_cvt_pk_bf16_f32 v42, v102, v103
	v_cvt_pk_bf16_f32 v43, v104, v105
	v_cvt_pk_bf16_f32 v44, v96, v97
	v_cvt_pk_bf16_f32 v45, v98, v99
	v_lshl_add_u64 v[48:49], v[78:79], 0, v[0:1]
	s_nop 0
	s_nop 1
	v_bfe_u32 v101, v227, 4, 2
	v_sub_u32_e32 v100, 0, v101
	v_lshlrev_b32_e32 v100, 4, v100
	v_ashrrev_i32_e32 v101, 31, v100
	v_lshl_add_u64 v[100:101], v[94:95], 0, v[100:101]
	v_permlane16_swap_b32_e32 v102, v96
	v_permlane16_swap_b32_e32 v103, v97
	v_permlane16_swap_b32_e32 v104, v98
	v_permlane16_swap_b32_e32 v105, v99
	v_permlane32_swap_b32_e32 v102, v96
	v_permlane32_swap_b32_e32 v103, v97
	v_permlane32_swap_b32_e32 v104, v98
	v_permlane32_swap_b32_e32 v105, v99
	v_mov_b32_e32 v108, v102
	v_mov_b32_e32 v109, v103
	v_mov_b32_e32 v110, v104
	v_mov_b32_e32 v111, v105
	v_bfe_u32 v106, v227, 3, 1
	v_mul_i32_i24_e32 v106, 0xffff8040, v106
	v_ashrrev_i32_e32 v107, 31, v106
	v_lshl_add_u64 v[100:101], v[100:101], 0, v[106:107]
	v_mov_b32_e32 v106, 0x8000
	v_mov_b32_e32 v107, 0
	v_lshl_add_u64 v[106:107], v[100:101], 0, v[106:107]
	v_mov_b32_dpp v102, v96 row_ror:8 row_mask:0xf bank_mask:0xc
	v_mov_b32_dpp v103, v97 row_ror:8 row_mask:0xf bank_mask:0xc
	v_mov_b32_dpp v104, v98 row_ror:8 row_mask:0xf bank_mask:0xc
	v_mov_b32_dpp v105, v99 row_ror:8 row_mask:0xf bank_mask:0xc
	v_mov_b32_dpp v96, v108 row_ror:8 row_mask:0xf bank_mask:0x3
	v_mov_b32_dpp v97, v109 row_ror:8 row_mask:0xf bank_mask:0x3
	v_mov_b32_dpp v98, v110 row_ror:8 row_mask:0xf bank_mask:0x3
	v_mov_b32_dpp v99, v111 row_ror:8 row_mask:0xf bank_mask:0x3
	global_store_dwordx4 v[100:101], v[102:105], off
	global_store_dwordx4 v[106:107], v[96:99], off
	s_nop 1
	global_store_dwordx4 v[48:49], v[42:45], off
	s_waitcnt vmcnt(7)
	s_nop 0
	v_sub_f32_e32 v43, v73, v93
	v_sub_f32_e32 v42, v72, v93
	v_sub_f32_e32 v45, v71, v93
	v_sub_f32_e32 v44, v70, v93
	v_pk_mul_f32 v[44:45], v[92:93], v[44:45] op_sel_hi:[0,1]
	v_pk_mul_f32 v[42:43], v[92:93], v[42:43] op_sel_hi:[0,1]
	s_waitcnt vmcnt(3)
; __device__ __forceinline__ float xsum16(float v) { const auto r = __builtin_amdgcn_permlane16_swap(__float_as_uint(v), __float_as_uint(v), false, false); return __uint_as_float(r[0]) + __uint_as_float(r[1]); }
; __device__ __forceinline__ float xsum32(float v) { const auto r = __builtin_amdgcn_permlane32_swap(__float_as_uint(v), __float_as_uint(v), false, false); return __uint_as_float(r[0]) + __uint_as_float(r[1]); }
; __device__ __forceinline__ size_t blk_off(int r, int c, int K) { return (size_t)(r >> 8) * 256 * K + (size_t)(c >> 6) * (256 * 64) + (size_t)((r & 255) * 64 + (c & 63)); }
; __device__ __forceinline__ u32x4 pack8(const f32x4 a, const f32x4 b) { u32x4 w; w.x = cvt_pk_bf16(a[0], a[1]); w.y = cvt_pk_bf16(a[2], a[3]); w.z = cvt_pk_bf16(b[0], b[1]); w.w = cvt_pk_bf16(b[2], b[3]); return w; }
;     __device__ __forceinline__ void operator()(const f32x4 (&acc)[2][2][4][2], const pg8::Unit& u, int wr, int wc, int fr, int fq) const {
;     ...
;                 for (int bj = 0; bj < 2; ++bj) { float* yp = Y + (size_t)row * D_ + col0 + bj * 128; f32x4 v[2];
; #pragma unroll
;                     for (int n = 0; n < 2; ++n) { v[n] = (((yv[bj][n] - mu) * rs) * gq[bj][n] + bq_[bj][n]) * ALPHA_ + acc[ai][bj][m][n] * sc;
;                         *(f32x4*)(yp + 4 * n) = v[n]; s1 += (v[n][0] + v[n][1]) + (v[n][2] + v[n][3]); s2 += (v[n][0] * v[n][0] + v[n][1] * v[n][1]) + (v[n][2] * v[n][2] + v[n][3] * v[n][3]); }
;                     *(u32x4*)(Yb + blk_off(row, col0 + bj * 128, D_)) = pack8(v[0], v[1]); }
;                 s1 = xsum32(xsum16(s1)); s2 = xsum32(xsum16(s2));
;                 if (fq == 0) *(f32x2*)(stn + (size_t)row * 32 + (u.pn * 4 + wc) * 2) = (f32x2){s1, s2}; asm volatile("" ::: "memory"); } }
	v_pk_fma_f32 v[42:43], v[64:65], v[42:43], v[68:69]
	v_pk_fma_f32 v[44:45], v[62:63], v[44:45], v[66:67]
	v_pk_mul_f32 v[42:43], v[42:43], s[2:3] op_sel_hi:[1,0]
	v_pk_mul_f32 v[44:45], v[44:45], s[2:3] op_sel_hi:[1,0]
	v_pk_fma_f32 v[40:41], v[40:41], 0.5, v[42:43] op_sel_hi:[1,0,1]
	v_pk_fma_f32 v[38:39], v[38:39], 0.5, v[44:45] op_sel_hi:[1,0,1]
	v_add_f32_e32 v43, v40, v41
	v_add_f32_e32 v42, v38, v39
	v_add_f32_e32 v42, v42, v43
	v_add_f32_e32 v47, v47, v42
	v_mul_f32_e32 v42, v39, v39
	v_mul_f32_e32 v43, v41, v41
	v_fmac_f32_e32 v42, v38, v38
	v_fmac_f32_e32 v43, v40, v40
	v_add_f32_e32 v42, v42, v43
	v_add_f32_e32 v46, v46, v42
	v_sub_f32_e32 v43, v53, v93
	v_sub_f32_e32 v42, v52, v93
	v_sub_f32_e32 v45, v51, v93
	v_sub_f32_e32 v44, v50, v93
	v_pk_mul_f32 v[44:45], v[92:93], v[44:45] op_sel_hi:[0,1]
	v_pk_mul_f32 v[42:43], v[92:93], v[42:43] op_sel_hi:[0,1]
	v_pk_fma_f32 v[42:43], v[56:57], v[42:43], v[60:61]
	v_pk_fma_f32 v[44:45], v[54:55], v[44:45], v[58:59]
	v_pk_mul_f32 v[42:43], v[42:43], s[2:3] op_sel_hi:[1,0]
	v_pk_mul_f32 v[44:45], v[44:45], s[2:3] op_sel_hi:[1,0]
	v_pk_fma_f32 v[36:37], v[36:37], 0.5, v[42:43] op_sel_hi:[1,0,1]
	v_pk_fma_f32 v[34:35], v[34:35], 0.5, v[44:45] op_sel_hi:[1,0,1]
	v_add_f32_e32 v43, v36, v37
	v_add_f32_e32 v42, v34, v35
	v_add_f32_e32 v42, v42, v43
	v_mul_f32_e32 v43, v35, v35
	v_mul_f32_e32 v44, v37, v37
	v_add_f32_e32 v42, v47, v42
	v_fmac_f32_e32 v43, v34, v34
	v_fmac_f32_e32 v44, v36, v36
	s_nop 0
	s_nop 1
	v_bfe_u32 v49, v227, 4, 2
	v_sub_u32_e32 v48, 0, v49
	v_lshlrev_b32_e32 v48, 4, v48
	v_ashrrev_i32_e32 v49, 31, v48
	v_lshl_add_u64 v[48:49], v[94:95], 0, v[48:49]
	v_permlane16_swap_b32_e32 v38, v34
	v_permlane16_swap_b32_e32 v39, v35
	v_permlane16_swap_b32_e32 v40, v36
	v_permlane16_swap_b32_e32 v41, v37
	v_permlane32_swap_b32_e32 v38, v34
	v_permlane32_swap_b32_e32 v39, v35
	v_permlane32_swap_b32_e32 v40, v36
	v_permlane32_swap_b32_e32 v41, v37
	v_mov_b32_e32 v45, v38
	v_mov_b32_e32 v52, v39
	v_mov_b32_e32 v53, v40
	v_mov_b32_e32 v54, v41
	v_bfe_u32 v50, v227, 3, 1
	v_mul_i32_i24_e32 v50, 0xffff8040, v50
	v_ashrrev_i32_e32 v51, 31, v50
	v_lshl_add_u64 v[48:49], v[48:49], 0, v[50:51]
	v_mov_b32_e32 v50, 0x8000
	v_mov_b32_e32 v51, 0
	v_lshl_add_u64 v[50:51], v[48:49], 0, v[50:51]
	v_mov_b32_dpp v38, v34 row_ror:8 row_mask:0xf bank_mask:0xc
	v_mov_b32_dpp v39, v35 row_ror:8 row_mask:0xf bank_mask:0xc
	v_mov_b32_dpp v40, v36 row_ror:8 row_mask:0xf bank_mask:0xc
	v_mov_b32_dpp v41, v37 row_ror:8 row_mask:0xf bank_mask:0xc
	v_mov_b32_dpp v34, v45 row_ror:8 row_mask:0xf bank_mask:0x3
	v_mov_b32_dpp v35, v52 row_ror:8 row_mask:0xf bank_mask:0x3
	v_mov_b32_dpp v36, v53 row_ror:8 row_mask:0xf bank_mask:0x3
	v_mov_b32_dpp v37, v54 row_ror:8 row_mask:0xf bank_mask:0x3
	global_store_dwordx4 v[48:49], v[38:41], off offset:512
	global_store_dwordx4 v[50:51], v[34:37], off offset:512
	s_nop 1
	v_mov_b32_dpp v34, v38 row_ror:8 row_mask:0xf bank_mask:0x3
	v_mov_b32_dpp v35, v39 row_ror:8 row_mask:0xf bank_mask:0x3
	v_mov_b32_dpp v36, v40 row_ror:8 row_mask:0xf bank_mask:0x3
	v_mov_b32_dpp v37, v41 row_ror:8 row_mask:0xf bank_mask:0x3
	v_mov_b32_e32 v38, v45
	v_mov_b32_e32 v39, v52
	v_mov_b32_e32 v40, v53
	v_mov_b32_e32 v41, v54
	s_nop 1
	v_permlane32_swap_b32_e32 v38, v34
	v_permlane32_swap_b32_e32 v39, v35
	v_permlane32_swap_b32_e32 v40, v36
	v_permlane32_swap_b32_e32 v41, v37
	v_permlane16_swap_b32_e32 v38, v34
	v_permlane16_swap_b32_e32 v39, v35
	v_permlane16_swap_b32_e32 v40, v36
	v_permlane16_swap_b32_e32 v41, v37
	v_add_f32_e32 v43, v43, v44
	v_cvt_pk_bf16_f32 v38, v38, v39
	v_cvt_pk_bf16_f32 v39, v40, v41
	v_cvt_pk_bf16_f32 v40, v34, v35
	v_lshl_add_u64 v[34:35], v[76:77], 0, v[0:1]
	v_mov_b32_e32 v0, v42
	v_add_f32_e32 v43, v46, v43
	v_cvt_pk_bf16_f32 v41, v36, v37
	v_permlane16_swap_b32_e32 v42, v0
	global_store_dwordx4 v[34:35], v[38:41], off
	v_add_f32_e32 v34, v42, v0
	v_mov_b32_e32 v0, v43
	s_nop 1
	v_permlane16_swap_b32_e32 v43, v0
	v_add_f32_e32 v35, v43, v0
	v_mov_b32_e32 v36, v34
	v_mov_b32_e32 v37, v35
	s_nop 0
	v_permlane32_swap_b32_e32 v34, v36
	v_permlane32_swap_b32_e32 v35, v37
	s_and_saveexec_b64 s[24:25], s[40:41]
	s_cbranch_execz .LBB0_1715
	v_pk_add_f32 v[34:35], v[34:35], v[36:37]
	v_lshl_add_u64 v[36:37], s[8:9], 0, v[86:87]
	v_lshl_add_u64 v[36:37], s[38:39], 2, v[36:37]
	global_store_dwordx2 v[36:37], v[34:35], off
; __device__ __forceinline__ size_t blk_off(int r, int c, int K) { return (size_t)(r >> 8) * 256 * K + (size_t)(c >> 6) * (256 * 64) + (size_t)((r & 255) * 64 + (c & 63)); }
; __device__ __forceinline__ u32x4 pack8(const f32x4 a, const f32x4 b) { u32x4 w; w.x = cvt_pk_bf16(a[0], a[1]); w.y = cvt_pk_bf16(a[2], a[3]); w.z = cvt_pk_bf16(b[0], b[1]); w.w = cvt_pk_bf16(b[2], b[3]); return w; }
;     __device__ __forceinline__ void operator()(const f32x4 (&acc)[2][2][4][2], const pg8::Unit& u, int wr, int wc, int fr, int fq) const {
;     ...
;             for (int m = 0; m < 4; ++m) { const int row = row0 + ai * 128 + m * 16; const float mu = mu4[m], rs = rs4[m];
;                 f32x4 yv[2][2], gq[2][2], bq_[2][2];
; #pragma unroll
;                 for (int bj = 0; bj < 2; ++bj)
; #pragma unroll
;                     for (int n = 0; n < 2; ++n) { yv[bj][n] = *(const f32x4*)(Yin + (size_t)row * D_ + col0 + bj * 128 + 4 * n); gq[bj][n] = *(const f32x4*)(g + col0 + bj * 128 + 4 * n); bq_[bj][n] = *(const f32x4*)(b + col0 + bj * 128 + 4 * n); }
;                 asm volatile("" ::: "memory");
;                 float s1 = 0.f, s2 = 0.f;
; #pragma unroll
;                 for (int bj = 0; bj < 2; ++bj) { float* yp = Y + (size_t)row * D_ + col0 + bj * 128; f32x4 v[2];
; #pragma unroll
;                     for (int n = 0; n < 2; ++n) { v[n] = (((yv[bj][n] - mu) * rs) * gq[bj][n] + bq_[bj][n]) * ALPHA_ + acc[ai][bj][m][n] * sc;
;                         *(f32x4*)(yp + 4 * n) = v[n]; s1 += (v[n][0] + v[n][1]) + (v[n][2] + v[n][3]); s2 += (v[n][0] * v[n][0] + v[n][1] * v[n][1]) + (v[n][2] * v[n][2] + v[n][3] * v[n][3]); }
;                     *(u32x4*)(Yb + blk_off(row, col0 + bj * 128, D_)) = pack8(v[0], v[1]); }
.LBB0_1715:
	s_or_b64 exec, exec, s[24:25]
	v_pk_add_f32 v[34:35], v[88:89], v[90:91]
	s_mov_b32 s2, 0x3a800000
	v_pk_mul_f32 v[58:59], v[34:35], s[2:3] op_sel_hi:[1,0]
	s_mov_b32 s1, 0x800000
	v_fma_f32 v0, -v59, v59, v58
	v_max_f32_e32 v0, 0, v0
	v_add_f32_e32 v0, 0x3727c5ac, v0
	v_cmp_gt_f32_e32 vcc, s1, v0
	v_mul_f32_e32 v34, 0x4b800000, v0
	s_load_dwordx16 s[60:75], s[34:35], 0x38
	v_cndmask_b32_e32 v0, v0, v34, vcc
	v_rsq_f32_e32 v0, v0
	s_mov_b32 s2, 0x3fd744fd
	s_movk_i32 s1, 0x3bc0
	v_mul_f32_e32 v34, 0x45800000, v0
	v_cndmask_b32_e32 v58, v0, v34, vcc
	v_lshlrev_b64 v[34:35], 12, v[80:81]
	s_waitcnt lgkmcnt(0)
	v_lshl_add_u64 v[34:35], s[74:75], 0, v[34:35]
	v_lshl_add_u64 v[60:61], v[152:153], 2, v[34:35]
	global_load_dwordx4 v[62:65], v[60:61], off offset:16
	global_load_dwordx4 v[66:69], v[60:61], off
	global_load_dwordx4 v[70:73], v[156:157], off offset:16
	global_load_dwordx4 v[86:89], v[156:157], off
	global_load_dwordx4 v[90:93], v[154:155], off offset:16
	global_load_dwordx4 v[94:97], v[154:155], off
	global_load_dwordx4 v[34:37], v[60:61], off offset:528
	global_load_dwordx4 v[54:57], v[60:61], off offset:512
	global_load_dwordx4 v[38:41], v[156:157], off offset:528
	global_load_dwordx4 v[46:49], v[156:157], off offset:512
	global_load_dwordx4 v[42:45], v[154:155], off offset:528
	global_load_dwordx4 v[50:53], v[154:155], off offset:512
	v_lshlrev_b32_e32 v0, 6, v80
	v_and_or_b32 v0, v0, s1, v196
	v_lshlrev_b32_e32 v0, 1, v0
	s_waitcnt vmcnt(10)
	v_sub_f32_e32 v69, v69, v59
	v_sub_f32_e32 v68, v68, v59
	v_sub_f32_e32 v67, v67, v59
	v_sub_f32_e32 v66, v66, v59
	v_pk_mul_f32 v[66:67], v[58:59], v[66:67] op_sel_hi:[0,1]
	v_pk_mul_f32 v[68:69], v[58:59], v[68:69] op_sel_hi:[0,1]
	s_waitcnt vmcnt(6)
	v_pk_fma_f32 v[68:69], v[88:89], v[68:69], v[96:97]
	v_pk_fma_f32 v[66:67], v[86:87], v[66:67], v[94:95]
	v_pk_mul_f32 v[68:69], v[68:69], s[2:3] op_sel_hi:[1,0]
	v_pk_mul_f32 v[66:67], v[66:67], s[2:3] op_sel_hi:[1,0]
	v_pk_fma_f32 v[68:69], v[32:33], 0.5, v[68:69] op_sel_hi:[1,0,1]
	v_pk_fma_f32 v[66:67], v[30:31], 0.5, v[66:67] op_sel_hi:[1,0,1]
	v_add_f32_e32 v31, v68, v69
	v_add_f32_e32 v30, v66, v67
	v_add_f32_e32 v30, v30, v31
	v_add_f32_e32 v86, 0, v30
	v_mul_f32_e32 v30, v67, v67
	v_mul_f32_e32 v31, v69, v69
	v_fmac_f32_e32 v30, v66, v66
	v_fmac_f32_e32 v31, v68, v68
	v_add_f32_e32 v87, v30, v31
	v_sub_f32_e32 v31, v65, v59
	v_sub_f32_e32 v30, v64, v59
	v_sub_f32_e32 v33, v63, v59
	v_sub_f32_e32 v32, v62, v59
	v_pk_mul_f32 v[32:33], v[58:59], v[32:33] op_sel_hi:[0,1]
	v_pk_mul_f32 v[30:31], v[58:59], v[30:31] op_sel_hi:[0,1]
	v_pk_fma_f32 v[30:31], v[72:73], v[30:31], v[92:93]
	v_pk_fma_f32 v[32:33], v[70:71], v[32:33], v[90:91]
	v_pk_mul_f32 v[30:31], v[30:31], s[2:3] op_sel_hi:[1,0]
	v_pk_mul_f32 v[32:33], v[32:33], s[2:3] op_sel_hi:[1,0]
	v_pk_fma_f32 v[64:65], v[28:29], 0.5, v[30:31] op_sel_hi:[1,0,1]
	v_pk_fma_f32 v[62:63], v[26:27], 0.5, v[32:33] op_sel_hi:[1,0,1]
	v_add_f32_e32 v27, v64, v65
	v_add_f32_e32 v26, v62, v63
	v_add_f32_e32 v26, v26, v27
	v_add_f32_e32 v31, v86, v26
	v_mul_f32_e32 v26, v63, v63
	v_mul_f32_e32 v27, v65, v65
	v_fmac_f32_e32 v26, v62, v62
	v_fmac_f32_e32 v27, v64, v64
	v_add_f32_e32 v26, v26, v27
	v_add_f32_e32 v30, v87, v26
	v_cvt_pk_bf16_f32 v26, v66, v67
	v_cvt_pk_bf16_f32 v27, v68, v69
	v_cvt_pk_bf16_f32 v28, v62, v63
	v_cvt_pk_bf16_f32 v29, v64, v65
	v_lshl_add_u64 v[32:33], v[78:79], 0, v[0:1]
	s_nop 0
	s_nop 1
	v_bfe_u32 v71, v227, 4, 2
	v_sub_u32_e32 v70, 0, v71
	v_lshlrev_b32_e32 v70, 4, v70
	v_ashrrev_i32_e32 v71, 31, v70
	v_lshl_add_u64 v[70:71], v[60:61], 0, v[70:71]
	v_permlane16_swap_b32_e32 v66, v62
	v_permlane16_swap_b32_e32 v67, v63
	v_permlane16_swap_b32_e32 v68, v64
	v_permlane16_swap_b32_e32 v69, v65
	v_permlane32_swap_b32_e32 v66, v62
	v_permlane32_swap_b32_e32 v67, v63
	v_permlane32_swap_b32_e32 v68, v64
	v_permlane32_swap_b32_e32 v69, v65
	v_mov_b32_e32 v86, v66
	v_mov_b32_e32 v87, v67
	v_mov_b32_e32 v88, v68
	v_mov_b32_e32 v89, v69
	v_bfe_u32 v72, v227, 3, 1
	v_mul_i32_i24_e32 v72, 0xffff8040, v72
	v_ashrrev_i32_e32 v73, 31, v72
	v_lshl_add_u64 v[70:71], v[70:71], 0, v[72:73]
	v_mov_b32_e32 v72, 0x8000
	v_mov_b32_e32 v73, 0
	v_lshl_add_u64 v[72:73], v[70:71], 0, v[72:73]
	v_mov_b32_dpp v66, v62 row_ror:8 row_mask:0xf bank_mask:0xc
	v_mov_b32_dpp v67, v63 row_ror:8 row_mask:0xf bank_mask:0xc
	v_mov_b32_dpp v68, v64 row_ror:8 row_mask:0xf bank_mask:0xc
	v_mov_b32_dpp v69, v65 row_ror:8 row_mask:0xf bank_mask:0xc
	v_mov_b32_dpp v62, v86 row_ror:8 row_mask:0xf bank_mask:0x3
	v_mov_b32_dpp v63, v87 row_ror:8 row_mask:0xf bank_mask:0x3
	v_mov_b32_dpp v64, v88 row_ror:8 row_mask:0xf bank_mask:0x3
	v_mov_b32_dpp v65, v89 row_ror:8 row_mask:0xf bank_mask:0x3
	global_store_dwordx4 v[70:71], v[66:69], off
	global_store_dwordx4 v[72:73], v[62:65], off
	s_nop 1
	global_store_dwordx4 v[32:33], v[26:29], off
	s_waitcnt vmcnt(7)
	s_nop 0
	v_sub_f32_e32 v27, v57, v59
	v_sub_f32_e32 v26, v56, v59
	v_sub_f32_e32 v29, v55, v59
	v_sub_f32_e32 v28, v54, v59
	v_pk_mul_f32 v[28:29], v[58:59], v[28:29] op_sel_hi:[0,1]
	v_pk_mul_f32 v[26:27], v[58:59], v[26:27] op_sel_hi:[0,1]
	s_waitcnt vmcnt(3)
; __device__ __forceinline__ float xsum16(float v) { const auto r = __builtin_amdgcn_permlane16_swap(__float_as_uint(v), __float_as_uint(v), false, false); return __uint_as_float(r[0]) + __uint_as_float(r[1]); }
; __device__ __forceinline__ float xsum32(float v) { const auto r = __builtin_amdgcn_permlane32_swap(__float_as_uint(v), __float_as_uint(v), false, false); return __uint_as_float(r[0]) + __uint_as_float(r[1]); }
; __device__ __forceinline__ size_t blk_off(int r, int c, int K) { return (size_t)(r >> 8) * 256 * K + (size_t)(c >> 6) * (256 * 64) + (size_t)((r & 255) * 64 + (c & 63)); }
; __device__ __forceinline__ u32x4 pack8(const f32x4 a, const f32x4 b) { u32x4 w; w.x = cvt_pk_bf16(a[0], a[1]); w.y = cvt_pk_bf16(a[2], a[3]); w.z = cvt_pk_bf16(b[0], b[1]); w.w = cvt_pk_bf16(b[2], b[3]); return w; }
;     __device__ __forceinline__ void operator()(const f32x4 (&acc)[2][2][4][2], const pg8::Unit& u, int wr, int wc, int fr, int fq) const {
;     ...
;                 for (int bj = 0; bj < 2; ++bj) { float* yp = Y + (size_t)row * D_ + col0 + bj * 128; f32x4 v[2];
; #pragma unroll
;                     for (int n = 0; n < 2; ++n) { v[n] = (((yv[bj][n] - mu) * rs) * gq[bj][n] + bq_[bj][n]) * ALPHA_ + acc[ai][bj][m][n] * sc;
;                         *(f32x4*)(yp + 4 * n) = v[n]; s1 += (v[n][0] + v[n][1]) + (v[n][2] + v[n][3]); s2 += (v[n][0] * v[n][0] + v[n][1] * v[n][1]) + (v[n][2] * v[n][2] + v[n][3] * v[n][3]); }
;                     *(u32x4*)(Yb + blk_off(row, col0 + bj * 128, D_)) = pack8(v[0], v[1]); }
;                 s1 = xsum32(xsum16(s1)); s2 = xsum32(xsum16(s2));
;                 if (fq == 0) *(f32x2*)(stn + (size_t)row * 32 + (u.pn * 4 + wc) * 2) = (f32x2){s1, s2}; asm volatile("" ::: "memory"); } }
	v_pk_fma_f32 v[26:27], v[48:49], v[26:27], v[52:53]
	v_pk_fma_f32 v[28:29], v[46:47], v[28:29], v[50:51]
	v_pk_mul_f32 v[26:27], v[26:27], s[2:3] op_sel_hi:[1,0]
	v_pk_mul_f32 v[28:29], v[28:29], s[2:3] op_sel_hi:[1,0]
	v_pk_fma_f32 v[24:25], v[24:25], 0.5, v[26:27] op_sel_hi:[1,0,1]
	v_pk_fma_f32 v[22:23], v[22:23], 0.5, v[28:29] op_sel_hi:[1,0,1]
	v_add_f32_e32 v27, v24, v25
	v_add_f32_e32 v26, v22, v23
	v_add_f32_e32 v26, v26, v27
	v_add_f32_e32 v31, v31, v26
	v_mul_f32_e32 v26, v23, v23
	v_mul_f32_e32 v27, v25, v25
	v_fmac_f32_e32 v26, v22, v22
	v_fmac_f32_e32 v27, v24, v24
	v_add_f32_e32 v26, v26, v27
	v_add_f32_e32 v30, v30, v26
	v_sub_f32_e32 v27, v37, v59
	v_sub_f32_e32 v26, v36, v59
	v_sub_f32_e32 v29, v35, v59
	v_sub_f32_e32 v28, v34, v59
	v_pk_mul_f32 v[28:29], v[58:59], v[28:29] op_sel_hi:[0,1]
	v_pk_mul_f32 v[26:27], v[58:59], v[26:27] op_sel_hi:[0,1]
	v_pk_fma_f32 v[26:27], v[40:41], v[26:27], v[44:45]
	v_pk_fma_f32 v[28:29], v[38:39], v[28:29], v[42:43]
	v_pk_mul_f32 v[26:27], v[26:27], s[2:3] op_sel_hi:[1,0]
	v_pk_mul_f32 v[28:29], v[28:29], s[2:3] op_sel_hi:[1,0]
	v_pk_fma_f32 v[20:21], v[20:21], 0.5, v[26:27] op_sel_hi:[1,0,1]
	v_pk_fma_f32 v[18:19], v[18:19], 0.5, v[28:29] op_sel_hi:[1,0,1]
	v_add_f32_e32 v27, v20, v21
	v_add_f32_e32 v26, v18, v19
	v_add_f32_e32 v26, v26, v27
	v_mul_f32_e32 v27, v19, v19
	v_mul_f32_e32 v28, v21, v21
	v_add_f32_e32 v26, v31, v26
	v_fmac_f32_e32 v27, v18, v18
	v_fmac_f32_e32 v28, v20, v20
	s_nop 0
	s_nop 1
	v_bfe_u32 v33, v227, 4, 2
	v_sub_u32_e32 v32, 0, v33
	v_lshlrev_b32_e32 v32, 4, v32
	v_ashrrev_i32_e32 v33, 31, v32
	v_lshl_add_u64 v[32:33], v[60:61], 0, v[32:33]
	v_permlane16_swap_b32_e32 v22, v18
	v_permlane16_swap_b32_e32 v23, v19
	v_permlane16_swap_b32_e32 v24, v20
	v_permlane16_swap_b32_e32 v25, v21
	v_permlane32_swap_b32_e32 v22, v18
	v_permlane32_swap_b32_e32 v23, v19
	v_permlane32_swap_b32_e32 v24, v20
	v_permlane32_swap_b32_e32 v25, v21
	v_mov_b32_e32 v29, v22
	v_mov_b32_e32 v36, v23
	v_mov_b32_e32 v37, v24
	v_mov_b32_e32 v38, v25
	v_bfe_u32 v34, v227, 3, 1
	v_mul_i32_i24_e32 v34, 0xffff8040, v34
	v_ashrrev_i32_e32 v35, 31, v34
	v_lshl_add_u64 v[32:33], v[32:33], 0, v[34:35]
	v_mov_b32_e32 v34, 0x8000
	v_mov_b32_e32 v35, 0
	v_lshl_add_u64 v[34:35], v[32:33], 0, v[34:35]
	v_mov_b32_dpp v22, v18 row_ror:8 row_mask:0xf bank_mask:0xc
	v_mov_b32_dpp v23, v19 row_ror:8 row_mask:0xf bank_mask:0xc
	v_mov_b32_dpp v24, v20 row_ror:8 row_mask:0xf bank_mask:0xc
	v_mov_b32_dpp v25, v21 row_ror:8 row_mask:0xf bank_mask:0xc
	v_mov_b32_dpp v18, v29 row_ror:8 row_mask:0xf bank_mask:0x3
	v_mov_b32_dpp v19, v36 row_ror:8 row_mask:0xf bank_mask:0x3
	v_mov_b32_dpp v20, v37 row_ror:8 row_mask:0xf bank_mask:0x3
	v_mov_b32_dpp v21, v38 row_ror:8 row_mask:0xf bank_mask:0x3
	global_store_dwordx4 v[32:33], v[22:25], off offset:512
	global_store_dwordx4 v[34:35], v[18:21], off offset:512
	s_nop 1
	v_mov_b32_dpp v18, v22 row_ror:8 row_mask:0xf bank_mask:0x3
	v_mov_b32_dpp v19, v23 row_ror:8 row_mask:0xf bank_mask:0x3
	v_mov_b32_dpp v20, v24 row_ror:8 row_mask:0xf bank_mask:0x3
	v_mov_b32_dpp v21, v25 row_ror:8 row_mask:0xf bank_mask:0x3
	v_mov_b32_e32 v22, v29
	v_mov_b32_e32 v23, v36
	v_mov_b32_e32 v24, v37
	v_mov_b32_e32 v25, v38
	s_nop 1
	v_permlane32_swap_b32_e32 v22, v18
	v_permlane32_swap_b32_e32 v23, v19
	v_permlane32_swap_b32_e32 v24, v20
	v_permlane32_swap_b32_e32 v25, v21
	v_permlane16_swap_b32_e32 v22, v18
	v_permlane16_swap_b32_e32 v23, v19
	v_permlane16_swap_b32_e32 v24, v20
	v_permlane16_swap_b32_e32 v25, v21
	v_add_f32_e32 v27, v27, v28
	v_cvt_pk_bf16_f32 v22, v22, v23
	v_cvt_pk_bf16_f32 v23, v24, v25
	v_cvt_pk_bf16_f32 v24, v18, v19
	v_lshl_add_u64 v[18:19], v[76:77], 0, v[0:1]
	v_mov_b32_e32 v0, v26
	v_add_f32_e32 v27, v30, v27
	v_cvt_pk_bf16_f32 v25, v20, v21
	v_permlane16_swap_b32_e32 v26, v0
	global_store_dwordx4 v[18:19], v[22:25], off
	v_add_f32_e32 v18, v26, v0
	v_mov_b32_e32 v0, v27
	s_nop 1
	v_permlane16_swap_b32_e32 v27, v0
	v_add_f32_e32 v19, v27, v0
	v_mov_b32_e32 v20, v18
	v_mov_b32_e32 v21, v19
	s_nop 0
	v_permlane32_swap_b32_e32 v18, v20
	v_permlane32_swap_b32_e32 v19, v21
	s_and_saveexec_b64 s[24:25], s[40:41]
	s_cbranch_execz .LBB0_1717
	v_pk_add_f32 v[18:19], v[18:19], v[20:21]
	v_lshlrev_b64 v[20:21], 7, v[80:81]
	v_lshl_add_u64 v[20:21], s[8:9], 0, v[20:21]
	v_lshl_add_u64 v[20:21], s[38:39], 2, v[20:21]
	global_store_dwordx2 v[20:21], v[18:19], off
; __device__ __forceinline__ size_t blk_off(int r, int c, int K) { return (size_t)(r >> 8) * 256 * K + (size_t)(c >> 6) * (256 * 64) + (size_t)((r & 255) * 64 + (c & 63)); }
; __device__ __forceinline__ u32x4 pack8(const f32x4 a, const f32x4 b) { u32x4 w; w.x = cvt_pk_bf16(a[0], a[1]); w.y = cvt_pk_bf16(a[2], a[3]); w.z = cvt_pk_bf16(b[0], b[1]); w.w = cvt_pk_bf16(b[2], b[3]); return w; }
;     __device__ __forceinline__ void operator()(const f32x4 (&acc)[2][2][4][2], const pg8::Unit& u, int wr, int wc, int fr, int fq) const {
;     ...
;             for (int m = 0; m < 4; ++m) { const int row = row0 + ai * 128 + m * 16; const float mu = mu4[m], rs = rs4[m];
;                 f32x4 yv[2][2], gq[2][2], bq_[2][2];
; #pragma unroll
;                 for (int bj = 0; bj < 2; ++bj)
; #pragma unroll
;                     for (int n = 0; n < 2; ++n) { yv[bj][n] = *(const f32x4*)(Yin + (size_t)row * D_ + col0 + bj * 128 + 4 * n); gq[bj][n] = *(const f32x4*)(g + col0 + bj * 128 + 4 * n); bq_[bj][n] = *(const f32x4*)(b + col0 + bj * 128 + 4 * n); }
;                 asm volatile("" ::: "memory");
;                 float s1 = 0.f, s2 = 0.f;
; #pragma unroll
;                 for (int bj = 0; bj < 2; ++bj) { float* yp = Y + (size_t)row * D_ + col0 + bj * 128; f32x4 v[2];
; #pragma unroll
;                     for (int n = 0; n < 2; ++n) { v[n] = (((yv[bj][n] - mu) * rs) * gq[bj][n] + bq_[bj][n]) * ALPHA_ + acc[ai][bj][m][n] * sc;
;                         *(f32x4*)(yp + 4 * n) = v[n]; s1 += (v[n][0] + v[n][1]) + (v[n][2] + v[n][3]); s2 += (v[n][0] * v[n][0] + v[n][1] * v[n][1]) + (v[n][2] * v[n][2] + v[n][3] * v[n][3]); }
;                     *(u32x4*)(Yb + blk_off(row, col0 + bj * 128, D_)) = pack8(v[0], v[1]); }
.LBB0_1717:
	s_or_b64 exec, exec, s[24:25]
	v_pk_add_f32 v[18:19], v[82:83], v[84:85]
	s_mov_b32 s2, 0x3a800000
	v_pk_mul_f32 v[42:43], v[18:19], s[2:3] op_sel_hi:[1,0]
	s_mov_b32 s1, 0x800000
	v_fma_f32 v0, -v43, v43, v42
	v_max_f32_e32 v0, 0, v0
	v_add_f32_e32 v0, 0x3727c5ac, v0
	v_cmp_gt_f32_e32 vcc, s1, v0
	v_mul_f32_e32 v18, 0x4b800000, v0
	s_load_dwordx16 s[60:75], s[34:35], 0x38
	v_cndmask_b32_e32 v0, v0, v18, vcc
	v_rsq_f32_e32 v0, v0
	s_mov_b32 s2, 0x3fd744fd
	s_movk_i32 s1, 0x3fc0
	v_mul_f32_e32 v18, 0x45800000, v0
	v_cndmask_b32_e32 v42, v0, v18, vcc
	v_lshlrev_b64 v[18:19], 12, v[74:75]
	s_waitcnt lgkmcnt(0)
	v_lshl_add_u64 v[18:19], s[74:75], 0, v[18:19]
	v_lshl_add_u64 v[44:45], v[152:153], 2, v[18:19]
	global_load_dwordx4 v[46:49], v[44:45], off offset:16
	global_load_dwordx4 v[50:53], v[44:45], off
	global_load_dwordx4 v[54:57], v[156:157], off offset:16
	global_load_dwordx4 v[58:61], v[156:157], off
	global_load_dwordx4 v[62:65], v[154:155], off offset:16
	global_load_dwordx4 v[66:69], v[154:155], off
	global_load_dwordx4 v[18:21], v[44:45], off offset:528
	global_load_dwordx4 v[38:41], v[44:45], off offset:512
	global_load_dwordx4 v[22:25], v[156:157], off offset:528
	global_load_dwordx4 v[30:33], v[156:157], off offset:512
	global_load_dwordx4 v[26:29], v[154:155], off offset:528
	global_load_dwordx4 v[34:37], v[154:155], off offset:512
	v_lshlrev_b32_e32 v0, 6, v74
	v_and_or_b32 v0, v0, s1, v196
	v_lshlrev_b32_e32 v0, 1, v0
	s_waitcnt vmcnt(10)
	v_sub_f32_e32 v53, v53, v43
	v_sub_f32_e32 v52, v52, v43
	v_sub_f32_e32 v51, v51, v43
	v_sub_f32_e32 v50, v50, v43
	v_pk_mul_f32 v[50:51], v[42:43], v[50:51] op_sel_hi:[0,1]
	v_pk_mul_f32 v[52:53], v[42:43], v[52:53] op_sel_hi:[0,1]
	s_waitcnt vmcnt(6)
	v_pk_fma_f32 v[52:53], v[60:61], v[52:53], v[68:69]
	v_pk_fma_f32 v[50:51], v[58:59], v[50:51], v[66:67]
	v_pk_mul_f32 v[52:53], v[52:53], s[2:3] op_sel_hi:[1,0]
	v_pk_mul_f32 v[50:51], v[50:51], s[2:3] op_sel_hi:[1,0]
	v_pk_fma_f32 v[52:53], v[16:17], 0.5, v[52:53] op_sel_hi:[1,0,1]
	v_pk_fma_f32 v[50:51], v[14:15], 0.5, v[50:51] op_sel_hi:[1,0,1]
	v_add_f32_e32 v15, v52, v53
	v_add_f32_e32 v14, v50, v51
	v_add_f32_e32 v14, v14, v15
	v_add_f32_e32 v58, 0, v14
	v_mul_f32_e32 v14, v51, v51
	v_mul_f32_e32 v15, v53, v53
	v_fmac_f32_e32 v14, v50, v50
	v_fmac_f32_e32 v15, v52, v52
	v_add_f32_e32 v59, v14, v15
	v_sub_f32_e32 v15, v49, v43
	v_sub_f32_e32 v14, v48, v43
	v_sub_f32_e32 v17, v47, v43
	v_sub_f32_e32 v16, v46, v43
	v_pk_mul_f32 v[16:17], v[42:43], v[16:17] op_sel_hi:[0,1]
	v_pk_mul_f32 v[14:15], v[42:43], v[14:15] op_sel_hi:[0,1]
	v_pk_fma_f32 v[14:15], v[56:57], v[14:15], v[64:65]
	v_pk_fma_f32 v[16:17], v[54:55], v[16:17], v[62:63]
	v_pk_mul_f32 v[14:15], v[14:15], s[2:3] op_sel_hi:[1,0]
	v_pk_mul_f32 v[16:17], v[16:17], s[2:3] op_sel_hi:[1,0]
	v_pk_fma_f32 v[48:49], v[12:13], 0.5, v[14:15] op_sel_hi:[1,0,1]
	v_pk_fma_f32 v[46:47], v[10:11], 0.5, v[16:17] op_sel_hi:[1,0,1]
	v_add_f32_e32 v11, v48, v49
	v_add_f32_e32 v10, v46, v47
	v_add_f32_e32 v10, v10, v11
	v_add_f32_e32 v15, v58, v10
	v_mul_f32_e32 v10, v47, v47
	v_mul_f32_e32 v11, v49, v49
	v_fmac_f32_e32 v10, v46, v46
	v_fmac_f32_e32 v11, v48, v48
	v_add_f32_e32 v10, v10, v11
	v_add_f32_e32 v14, v59, v10
	v_cvt_pk_bf16_f32 v10, v50, v51
	v_cvt_pk_bf16_f32 v11, v52, v53
	v_cvt_pk_bf16_f32 v12, v46, v47
	v_cvt_pk_bf16_f32 v13, v48, v49
	v_lshl_add_u64 v[16:17], v[78:79], 0, v[0:1]
	s_nop 0
	s_nop 1
	v_bfe_u32 v55, v227, 4, 2
	v_sub_u32_e32 v54, 0, v55
	v_lshlrev_b32_e32 v54, 4, v54
	v_ashrrev_i32_e32 v55, 31, v54
	v_lshl_add_u64 v[54:55], v[44:45], 0, v[54:55]
	v_permlane16_swap_b32_e32 v50, v46
	v_permlane16_swap_b32_e32 v51, v47
	v_permlane16_swap_b32_e32 v52, v48
	v_permlane16_swap_b32_e32 v53, v49
	v_permlane32_swap_b32_e32 v50, v46
	v_permlane32_swap_b32_e32 v51, v47
	v_permlane32_swap_b32_e32 v52, v48
	v_permlane32_swap_b32_e32 v53, v49
	v_mov_b32_e32 v58, v50
	v_mov_b32_e32 v59, v51
	v_mov_b32_e32 v60, v52
	v_mov_b32_e32 v61, v53
	v_bfe_u32 v56, v227, 3, 1
	v_mul_i32_i24_e32 v56, 0xffff8040, v56
	v_ashrrev_i32_e32 v57, 31, v56
	v_lshl_add_u64 v[54:55], v[54:55], 0, v[56:57]
	v_mov_b32_e32 v56, 0x8000
	v_mov_b32_e32 v57, 0
	v_lshl_add_u64 v[56:57], v[54:55], 0, v[56:57]
	v_mov_b32_dpp v50, v46 row_ror:8 row_mask:0xf bank_mask:0xc
	v_mov_b32_dpp v51, v47 row_ror:8 row_mask:0xf bank_mask:0xc
	v_mov_b32_dpp v52, v48 row_ror:8 row_mask:0xf bank_mask:0xc
	v_mov_b32_dpp v53, v49 row_ror:8 row_mask:0xf bank_mask:0xc
	v_mov_b32_dpp v46, v58 row_ror:8 row_mask:0xf bank_mask:0x3
	v_mov_b32_dpp v47, v59 row_ror:8 row_mask:0xf bank_mask:0x3
	v_mov_b32_dpp v48, v60 row_ror:8 row_mask:0xf bank_mask:0x3
	v_mov_b32_dpp v49, v61 row_ror:8 row_mask:0xf bank_mask:0x3
	global_store_dwordx4 v[54:55], v[50:53], off
	global_store_dwordx4 v[56:57], v[46:49], off
	s_nop 1
	global_store_dwordx4 v[16:17], v[10:13], off
	s_waitcnt vmcnt(7)
; __device__ __forceinline__ float xsum16(float v) { const auto r = __builtin_amdgcn_permlane16_swap(__float_as_uint(v), __float_as_uint(v), false, false); return __uint_as_float(r[0]) + __uint_as_float(r[1]); }
; __device__ __forceinline__ float xsum32(float v) { const auto r = __builtin_amdgcn_permlane32_swap(__float_as_uint(v), __float_as_uint(v), false, false); return __uint_as_float(r[0]) + __uint_as_float(r[1]); }
; __device__ __forceinline__ size_t blk_off(int r, int c, int K) { return (size_t)(r >> 8) * 256 * K + (size_t)(c >> 6) * (256 * 64) + (size_t)((r & 255) * 64 + (c & 63)); }
; __device__ __forceinline__ u32x4 pack8(const f32x4 a, const f32x4 b) { u32x4 w; w.x = cvt_pk_bf16(a[0], a[1]); w.y = cvt_pk_bf16(a[2], a[3]); w.z = cvt_pk_bf16(b[0], b[1]); w.w = cvt_pk_bf16(b[2], b[3]); return w; }
;     __device__ __forceinline__ void operator()(const f32x4 (&acc)[2][2][4][2], const pg8::Unit& u, int wr, int wc, int fr, int fq) const {
;     ...
;                 for (int bj = 0; bj < 2; ++bj) { float* yp = Y + (size_t)row * D_ + col0 + bj * 128; f32x4 v[2];
; #pragma unroll
;                     for (int n = 0; n < 2; ++n) { v[n] = (((yv[bj][n] - mu) * rs) * gq[bj][n] + bq_[bj][n]) * ALPHA_ + acc[ai][bj][m][n] * sc;
;                         *(f32x4*)(yp + 4 * n) = v[n]; s1 += (v[n][0] + v[n][1]) + (v[n][2] + v[n][3]); s2 += (v[n][0] * v[n][0] + v[n][1] * v[n][1]) + (v[n][2] * v[n][2] + v[n][3] * v[n][3]); }
;                     *(u32x4*)(Yb + blk_off(row, col0 + bj * 128, D_)) = pack8(v[0], v[1]); }
;                 s1 = xsum32(xsum16(s1)); s2 = xsum32(xsum16(s2));
;                 if (fq == 0) *(f32x2*)(stn + (size_t)row * 32 + (u.pn * 4 + wc) * 2) = (f32x2){s1, s2}; asm volatile("" ::: "memory"); } }
	s_nop 0
	v_sub_f32_e32 v11, v41, v43
	v_sub_f32_e32 v10, v40, v43
	v_sub_f32_e32 v13, v39, v43
	v_sub_f32_e32 v12, v38, v43
	v_pk_mul_f32 v[12:13], v[42:43], v[12:13] op_sel_hi:[0,1]
	v_pk_mul_f32 v[10:11], v[42:43], v[10:11] op_sel_hi:[0,1]
	s_waitcnt vmcnt(3)
	v_pk_fma_f32 v[10:11], v[32:33], v[10:11], v[36:37]
	v_pk_fma_f32 v[12:13], v[30:31], v[12:13], v[34:35]
	v_pk_mul_f32 v[10:11], v[10:11], s[2:3] op_sel_hi:[1,0]
	v_pk_mul_f32 v[12:13], v[12:13], s[2:3] op_sel_hi:[1,0]
	v_pk_fma_f32 v[8:9], v[8:9], 0.5, v[10:11] op_sel_hi:[1,0,1]
	v_pk_fma_f32 v[6:7], v[6:7], 0.5, v[12:13] op_sel_hi:[1,0,1]
	v_add_f32_e32 v11, v8, v9
	v_add_f32_e32 v10, v6, v7
	v_add_f32_e32 v10, v10, v11
	v_add_f32_e32 v15, v15, v10
	v_mul_f32_e32 v10, v7, v7
	v_mul_f32_e32 v11, v9, v9
	v_fmac_f32_e32 v10, v6, v6
	v_fmac_f32_e32 v11, v8, v8
	v_add_f32_e32 v10, v10, v11
	v_add_f32_e32 v14, v14, v10
	v_sub_f32_e32 v11, v21, v43
	v_sub_f32_e32 v10, v20, v43
	v_sub_f32_e32 v13, v19, v43
	v_sub_f32_e32 v12, v18, v43
	v_pk_mul_f32 v[12:13], v[42:43], v[12:13] op_sel_hi:[0,1]
	v_pk_mul_f32 v[10:11], v[42:43], v[10:11] op_sel_hi:[0,1]
	v_pk_fma_f32 v[10:11], v[24:25], v[10:11], v[28:29]
	v_pk_fma_f32 v[12:13], v[22:23], v[12:13], v[26:27]
	v_pk_mul_f32 v[10:11], v[10:11], s[2:3] op_sel_hi:[1,0]
	v_pk_mul_f32 v[12:13], v[12:13], s[2:3] op_sel_hi:[1,0]
	v_pk_fma_f32 v[4:5], v[4:5], 0.5, v[10:11] op_sel_hi:[1,0,1]
	v_pk_fma_f32 v[2:3], v[2:3], 0.5, v[12:13] op_sel_hi:[1,0,1]
	v_add_f32_e32 v11, v4, v5
	v_add_f32_e32 v10, v2, v3
	v_add_f32_e32 v10, v10, v11
	v_mul_f32_e32 v11, v3, v3
	v_mul_f32_e32 v12, v5, v5
	v_add_f32_e32 v10, v15, v10
	v_fmac_f32_e32 v11, v2, v2
	v_fmac_f32_e32 v12, v4, v4
	s_nop 0
	s_nop 1
	v_bfe_u32 v17, v227, 4, 2
	v_sub_u32_e32 v16, 0, v17
	v_lshlrev_b32_e32 v16, 4, v16
	v_ashrrev_i32_e32 v17, 31, v16
	v_lshl_add_u64 v[16:17], v[44:45], 0, v[16:17]
	v_permlane16_swap_b32_e32 v6, v2
	v_permlane16_swap_b32_e32 v7, v3
	v_permlane16_swap_b32_e32 v8, v4
	v_permlane16_swap_b32_e32 v9, v5
	v_permlane32_swap_b32_e32 v6, v2
	v_permlane32_swap_b32_e32 v7, v3
	v_permlane32_swap_b32_e32 v8, v4
	v_permlane32_swap_b32_e32 v9, v5
	v_mov_b32_e32 v13, v6
	v_mov_b32_e32 v20, v7
	v_mov_b32_e32 v21, v8
	v_mov_b32_e32 v22, v9
	v_bfe_u32 v18, v227, 3, 1
	v_mul_i32_i24_e32 v18, 0xffff8040, v18
	v_ashrrev_i32_e32 v19, 31, v18
	v_lshl_add_u64 v[16:17], v[16:17], 0, v[18:19]
	v_mov_b32_e32 v18, 0x8000
	v_mov_b32_e32 v19, 0
	v_lshl_add_u64 v[18:19], v[16:17], 0, v[18:19]
	v_mov_b32_dpp v6, v2 row_ror:8 row_mask:0xf bank_mask:0xc
	v_mov_b32_dpp v7, v3 row_ror:8 row_mask:0xf bank_mask:0xc
	v_mov_b32_dpp v8, v4 row_ror:8 row_mask:0xf bank_mask:0xc
	v_mov_b32_dpp v9, v5 row_ror:8 row_mask:0xf bank_mask:0xc
	v_mov_b32_dpp v2, v13 row_ror:8 row_mask:0xf bank_mask:0x3
	v_mov_b32_dpp v3, v20 row_ror:8 row_mask:0xf bank_mask:0x3
	v_mov_b32_dpp v4, v21 row_ror:8 row_mask:0xf bank_mask:0x3
	v_mov_b32_dpp v5, v22 row_ror:8 row_mask:0xf bank_mask:0x3
	global_store_dwordx4 v[16:17], v[6:9], off offset:512
	global_store_dwordx4 v[18:19], v[2:5], off offset:512
	s_nop 1
	v_mov_b32_dpp v2, v6 row_ror:8 row_mask:0xf bank_mask:0x3
	v_mov_b32_dpp v3, v7 row_ror:8 row_mask:0xf bank_mask:0x3
	v_mov_b32_dpp v4, v8 row_ror:8 row_mask:0xf bank_mask:0x3
	v_mov_b32_dpp v5, v9 row_ror:8 row_mask:0xf bank_mask:0x3
	v_mov_b32_e32 v6, v13
	v_mov_b32_e32 v7, v20
	v_mov_b32_e32 v8, v21
	v_mov_b32_e32 v9, v22
	s_nop 1
	v_permlane32_swap_b32_e32 v6, v2
	v_permlane32_swap_b32_e32 v7, v3
	v_permlane32_swap_b32_e32 v8, v4
	v_permlane32_swap_b32_e32 v9, v5
	v_permlane16_swap_b32_e32 v6, v2
	v_permlane16_swap_b32_e32 v7, v3
	v_permlane16_swap_b32_e32 v8, v4
	v_permlane16_swap_b32_e32 v9, v5
	v_add_f32_e32 v11, v11, v12
	v_cvt_pk_bf16_f32 v6, v6, v7
	v_cvt_pk_bf16_f32 v7, v8, v9
	v_cvt_pk_bf16_f32 v8, v2, v3
	v_lshl_add_u64 v[2:3], v[76:77], 0, v[0:1]
	v_mov_b32_e32 v0, v10
	v_add_f32_e32 v11, v14, v11
	v_cvt_pk_bf16_f32 v9, v4, v5
	v_permlane16_swap_b32_e32 v10, v0
	global_store_dwordx4 v[2:3], v[6:9], off
	v_add_f32_e32 v2, v10, v0
	v_mov_b32_e32 v0, v11
	s_nop 1
	v_permlane16_swap_b32_e32 v11, v0
	v_add_f32_e32 v3, v11, v0
	v_mov_b32_e32 v4, v2
	v_mov_b32_e32 v5, v3
	s_nop 0
	v_permlane32_swap_b32_e32 v2, v4
	v_permlane32_swap_b32_e32 v3, v5
	s_and_saveexec_b64 s[24:25], s[40:41]
	s_cbranch_execz .LBB0_1719
	v_pk_add_f32 v[2:3], v[2:3], v[4:5]
	v_lshlrev_b64 v[4:5], 7, v[74:75]
	v_lshl_add_u64 v[4:5], s[8:9], 0, v[4:5]
	v_lshl_add_u64 v[4:5], s[38:39], 2, v[4:5]
	global_store_dwordx2 v[4:5], v[2:3], off
